# plus batched gate loads in the dense-attention item epilogue and batched loads in the MLA elementwise item
# speedup vs baseline: 1.0146x; 1.0146x over previous
; DI unsigned pack2(float a, float b) { f2_t v = {a, b}; bf2_t r = __builtin_convertvector(v, bf2_t); return __builtin_bit_cast(unsigned, r); }
; #define BLO(u) __uint_as_float((u) << 16)
; #define BHI(u) __uint_as_float((u) & 0xffff0000u)
; DI float frcp(float x) { return __builtin_amdgcn_rcpf(x); }
; template <int DQK, bool FIXEDM>
; DI void attn_dense_mfma(const bf16_t* Qb, int ldq, const bf16_t* Kb, int ldk, const bf16_t* Vb, int ldv, bf16_t* gate_io, char* smem, bool store, float mbound) {
;     ...
;   const float inv = frcp(half_swap_sum(l_run));
;   bf16_t* grow = gate_io + (size_t)(wid * 32 + r) * PW;
; #pragma unroll
;   for (int db = 0; db < 2; ++db)
; #pragma unroll
;     for (int g4 = 0; g4 < 4; ++g4) {
;       bf16_t* gp = grow + 32 * db + 8 * g4 + 4 * h;
;       uint2 u = *(const uint2*)gp;
;       float g[4] = {BLO(u.x), BHI(u.x), BLO(u.y), BHI(u.y)};
;       float y[4];
; #pragma unroll
;       for (int e = 0; e < 4; ++e) { float ov = db == 0 ? o0[4 * g4 + e] : o1[4 * g4 + e]; y[e] = ov * inv * g[e] * frcp(1.0f + __expf(-g[e])); }
;       uint2 w; w.x = pack2(y[0], y[1]); w.y = pack2(y[2], y[3]);
;       *(uint2*)gp = w;
.LBB0_163:
	s_lshl_b32 s0, s31, 1
	s_add_u32 s6, s58, s0
	s_addc_u32 s7, s59, 0
	s_lshl_b32 s0, s30, 7
	s_and_b32 s0, s0, 0xffffff00
	s_ashr_i32 s1, s0, 31
	s_lshl_b64 s[0:1], s[0:1], 1
	s_add_u32 s0, s6, s0
	s_addc_u32 s1, s7, s1
	v_readlane_b32 s6, v255, 22
	s_add_u32 s0, s0, s6
	s_addc_u32 s1, s1, 0
	v_lshl_add_u64 v[36:37], v[162:163], 1, s[0:1]
	v_mov_b32_e32 v167, v1
	v_lshl_add_u64 v[38:39], v[166:167], 1, v[36:37]
	s_mov_b64 s[0:1], 0x6ca5a00
	v_lshl_add_u64 v[36:37], v[38:39], 0, s[0:1]
	s_mov_b32 s0, 0x6ca5000
	v_add_co_u32_e32 v38, vcc, s0, v38
	s_nop 0
	v_addc_co_u32_e32 v39, vcc, 0, v39, vcc
	global_load_dwordx2 v[40:41], v[36:37], off offset:0
	global_load_dwordx2 v[42:43], v[36:37], off offset:16
	global_load_dwordx2 v[44:45], v[36:37], off offset:32
	global_load_dwordx2 v[46:47], v[36:37], off offset:48
	global_load_dwordx2 v[48:49], v[36:37], off offset:64
	global_load_dwordx2 v[50:51], v[36:37], off offset:80
	global_load_dwordx2 v[52:53], v[36:37], off offset:96
	global_load_dwordx2 v[54:55], v[36:37], off offset:112
	v_mul_f32_e32 v18, v18, v34
	v_mul_f32_e32 v19, v19, v34
	v_mul_f32_e32 v20, v20, v34
	v_mul_f32_e32 v21, v21, v34
	v_mul_f32_e32 v22, v22, v34
	v_mul_f32_e32 v23, v23, v34
	v_mul_f32_e32 v24, v24, v34
	v_mul_f32_e32 v25, v25, v34
	v_mul_f32_e32 v26, v26, v34
	v_mul_f32_e32 v27, v27, v34
	v_mul_f32_e32 v28, v28, v34
	v_mul_f32_e32 v29, v29, v34
	v_mul_f32_e32 v30, v30, v34
	v_mul_f32_e32 v31, v31, v34
	v_mul_f32_e32 v32, v32, v34
	v_mul_f32_e32 v33, v33, v34
	v_mul_f32_e32 v2, v2, v34
	v_mul_f32_e32 v3, v3, v34
	v_mul_f32_e32 v4, v4, v34
	v_mul_f32_e32 v5, v5, v34
	v_mul_f32_e32 v6, v6, v34
	v_mul_f32_e32 v7, v7, v34
	v_mul_f32_e32 v8, v8, v34
	v_mul_f32_e32 v9, v9, v34
	v_mul_f32_e32 v10, v10, v34
	v_mul_f32_e32 v11, v11, v34
	v_mul_f32_e32 v12, v12, v34
	v_mul_f32_e32 v13, v13, v34
	v_mul_f32_e32 v14, v14, v34
	v_mul_f32_e32 v15, v15, v34
	v_mul_f32_e32 v16, v16, v34
	v_mul_f32_e32 v17, v17, v34
	s_waitcnt vmcnt(7)
	v_lshlrev_b32_e32 v56, 16, v40
	v_and_b32_e32 v57, 0xffff0000, v40
	v_lshlrev_b32_e32 v58, 16, v41
	v_and_b32_e32 v59, 0xffff0000, v41
	v_mul_f32_e32 v60, 0xbfb8aa3b, v56
	v_mul_f32_e32 v61, 0xbfb8aa3b, v57
	v_mul_f32_e32 v62, 0xbfb8aa3b, v58
	v_mul_f32_e32 v63, 0xbfb8aa3b, v59
	v_exp_f32_e32 v60, v60
	v_exp_f32_e32 v61, v61
	v_exp_f32_e32 v62, v62
	v_exp_f32_e32 v63, v63
	v_add_f32_e32 v60, 1.0, v60
	v_add_f32_e32 v61, 1.0, v61
	v_add_f32_e32 v62, 1.0, v62
	v_add_f32_e32 v63, 1.0, v63
	v_rcp_f32_e32 v60, v60
	v_rcp_f32_e32 v61, v61
	v_rcp_f32_e32 v62, v62
	v_rcp_f32_e32 v63, v63
	v_mul_f32_e32 v18, v18, v56
	v_mul_f32_e32 v19, v19, v57
	v_mul_f32_e32 v20, v20, v58
	v_mul_f32_e32 v21, v21, v59
	v_mul_f32_e32 v18, v18, v60
	v_mul_f32_e32 v19, v19, v61
	v_mul_f32_e32 v20, v20, v62
	v_mul_f32_e32 v21, v21, v63
	v_cvt_pk_bf16_f32 v64, v18, v19
	v_cvt_pk_bf16_f32 v65, v20, v21
	global_store_dwordx2 v[36:37], v[64:65], off offset:0
	s_waitcnt vmcnt(7)
	v_lshlrev_b32_e32 v56, 16, v42
	v_and_b32_e32 v57, 0xffff0000, v42
	v_lshlrev_b32_e32 v58, 16, v43
	v_and_b32_e32 v59, 0xffff0000, v43
	v_mul_f32_e32 v60, 0xbfb8aa3b, v56
	v_mul_f32_e32 v61, 0xbfb8aa3b, v57
	v_mul_f32_e32 v62, 0xbfb8aa3b, v58
	v_mul_f32_e32 v63, 0xbfb8aa3b, v59
	v_exp_f32_e32 v60, v60
	v_exp_f32_e32 v61, v61
	v_exp_f32_e32 v62, v62
	v_exp_f32_e32 v63, v63
	v_add_f32_e32 v60, 1.0, v60
	v_add_f32_e32 v61, 1.0, v61
	v_add_f32_e32 v62, 1.0, v62
	v_add_f32_e32 v63, 1.0, v63
	v_rcp_f32_e32 v60, v60
	v_rcp_f32_e32 v61, v61
	v_rcp_f32_e32 v62, v62
	v_rcp_f32_e32 v63, v63
	v_mul_f32_e32 v22, v22, v56
	v_mul_f32_e32 v23, v23, v57
	v_mul_f32_e32 v24, v24, v58
	v_mul_f32_e32 v25, v25, v59
	v_mul_f32_e32 v22, v22, v60
	v_mul_f32_e32 v23, v23, v61
	v_mul_f32_e32 v24, v24, v62
	v_mul_f32_e32 v25, v25, v63
	v_cvt_pk_bf16_f32 v66, v22, v23
	v_cvt_pk_bf16_f32 v67, v24, v25
	global_store_dwordx2 v[36:37], v[66:67], off offset:16
	s_waitcnt vmcnt(7)
	v_lshlrev_b32_e32 v56, 16, v44
	v_and_b32_e32 v57, 0xffff0000, v44
	v_lshlrev_b32_e32 v58, 16, v45
	v_and_b32_e32 v59, 0xffff0000, v45
	v_mul_f32_e32 v60, 0xbfb8aa3b, v56
	v_mul_f32_e32 v61, 0xbfb8aa3b, v57
	v_mul_f32_e32 v62, 0xbfb8aa3b, v58
	v_mul_f32_e32 v63, 0xbfb8aa3b, v59
	v_exp_f32_e32 v60, v60
	v_exp_f32_e32 v61, v61
	v_exp_f32_e32 v62, v62
	v_exp_f32_e32 v63, v63
	v_add_f32_e32 v60, 1.0, v60
	v_add_f32_e32 v61, 1.0, v61
	v_add_f32_e32 v62, 1.0, v62
	v_add_f32_e32 v63, 1.0, v63
	v_rcp_f32_e32 v60, v60
	v_rcp_f32_e32 v61, v61
	v_rcp_f32_e32 v62, v62
	v_rcp_f32_e32 v63, v63
	v_mul_f32_e32 v26, v26, v56
	v_mul_f32_e32 v27, v27, v57
	v_mul_f32_e32 v28, v28, v58
	v_mul_f32_e32 v29, v29, v59
	v_mul_f32_e32 v26, v26, v60
	v_mul_f32_e32 v27, v27, v61
	v_mul_f32_e32 v28, v28, v62
	v_mul_f32_e32 v29, v29, v63
	v_cvt_pk_bf16_f32 v64, v26, v27
	v_cvt_pk_bf16_f32 v65, v28, v29
	global_store_dwordx2 v[36:37], v[64:65], off offset:32
	s_waitcnt vmcnt(7)
; DI unsigned pack2(float a, float b) { f2_t v = {a, b}; bf2_t r = __builtin_convertvector(v, bf2_t); return __builtin_bit_cast(unsigned, r); }
; #define BLO(u) __uint_as_float((u) << 16)
; #define BHI(u) __uint_as_float((u) & 0xffff0000u)
; DI float frcp(float x) { return __builtin_amdgcn_rcpf(x); }
; template <int DQK, bool FIXEDM>
; DI void attn_dense_mfma(const bf16_t* Qb, int ldq, const bf16_t* Kb, int ldk, const bf16_t* Vb, int ldv, bf16_t* gate_io, char* smem, bool store, float mbound) {
;     ...
; #pragma unroll
;   for (int db = 0; db < 2; ++db)
; #pragma unroll
;     for (int g4 = 0; g4 < 4; ++g4) {
;       bf16_t* gp = grow + 32 * db + 8 * g4 + 4 * h;
;       uint2 u = *(const uint2*)gp;
;       float g[4] = {BLO(u.x), BHI(u.x), BLO(u.y), BHI(u.y)};
;       float y[4];
; #pragma unroll
;       for (int e = 0; e < 4; ++e) { float ov = db == 0 ? o0[4 * g4 + e] : o1[4 * g4 + e]; y[e] = ov * inv * g[e] * frcp(1.0f + __expf(-g[e])); }
;       uint2 w; w.x = pack2(y[0], y[1]); w.y = pack2(y[2], y[3]);
;       *(uint2*)gp = w;
;     }
	v_lshlrev_b32_e32 v56, 16, v46
	v_and_b32_e32 v57, 0xffff0000, v46
	v_lshlrev_b32_e32 v58, 16, v47
	v_and_b32_e32 v59, 0xffff0000, v47
	v_mul_f32_e32 v60, 0xbfb8aa3b, v56
	v_mul_f32_e32 v61, 0xbfb8aa3b, v57
	v_mul_f32_e32 v62, 0xbfb8aa3b, v58
	v_mul_f32_e32 v63, 0xbfb8aa3b, v59
	v_exp_f32_e32 v60, v60
	v_exp_f32_e32 v61, v61
	v_exp_f32_e32 v62, v62
	v_exp_f32_e32 v63, v63
	v_add_f32_e32 v60, 1.0, v60
	v_add_f32_e32 v61, 1.0, v61
	v_add_f32_e32 v62, 1.0, v62
	v_add_f32_e32 v63, 1.0, v63
	v_rcp_f32_e32 v60, v60
	v_rcp_f32_e32 v61, v61
	v_rcp_f32_e32 v62, v62
	v_rcp_f32_e32 v63, v63
	v_mul_f32_e32 v30, v30, v56
	v_mul_f32_e32 v31, v31, v57
	v_mul_f32_e32 v32, v32, v58
	v_mul_f32_e32 v33, v33, v59
	v_mul_f32_e32 v30, v30, v60
	v_mul_f32_e32 v31, v31, v61
	v_mul_f32_e32 v32, v32, v62
	v_mul_f32_e32 v33, v33, v63
	v_cvt_pk_bf16_f32 v66, v30, v31
	v_cvt_pk_bf16_f32 v67, v32, v33
	global_store_dwordx2 v[36:37], v[66:67], off offset:48
	s_waitcnt vmcnt(7)
	v_lshlrev_b32_e32 v56, 16, v48
	v_and_b32_e32 v57, 0xffff0000, v48
	v_lshlrev_b32_e32 v58, 16, v49
	v_and_b32_e32 v59, 0xffff0000, v49
	v_mul_f32_e32 v60, 0xbfb8aa3b, v56
	v_mul_f32_e32 v61, 0xbfb8aa3b, v57
	v_mul_f32_e32 v62, 0xbfb8aa3b, v58
	v_mul_f32_e32 v63, 0xbfb8aa3b, v59
	v_exp_f32_e32 v60, v60
	v_exp_f32_e32 v61, v61
	v_exp_f32_e32 v62, v62
	v_exp_f32_e32 v63, v63
	v_add_f32_e32 v60, 1.0, v60
	v_add_f32_e32 v61, 1.0, v61
	v_add_f32_e32 v62, 1.0, v62
	v_add_f32_e32 v63, 1.0, v63
	v_rcp_f32_e32 v60, v60
	v_rcp_f32_e32 v61, v61
	v_rcp_f32_e32 v62, v62
	v_rcp_f32_e32 v63, v63
	v_mul_f32_e32 v2, v2, v56
	v_mul_f32_e32 v3, v3, v57
	v_mul_f32_e32 v4, v4, v58
	v_mul_f32_e32 v5, v5, v59
	v_mul_f32_e32 v2, v2, v60
	v_mul_f32_e32 v3, v3, v61
	v_mul_f32_e32 v4, v4, v62
	v_mul_f32_e32 v5, v5, v63
	v_cvt_pk_bf16_f32 v64, v2, v3
	v_cvt_pk_bf16_f32 v65, v4, v5
	global_store_dwordx2 v[36:37], v[64:65], off offset:64
	s_waitcnt vmcnt(7)
	v_lshlrev_b32_e32 v56, 16, v50
	v_and_b32_e32 v57, 0xffff0000, v50
	v_lshlrev_b32_e32 v58, 16, v51
	v_and_b32_e32 v59, 0xffff0000, v51
	v_mul_f32_e32 v60, 0xbfb8aa3b, v56
	v_mul_f32_e32 v61, 0xbfb8aa3b, v57
	v_mul_f32_e32 v62, 0xbfb8aa3b, v58
	v_mul_f32_e32 v63, 0xbfb8aa3b, v59
	v_exp_f32_e32 v60, v60
	v_exp_f32_e32 v61, v61
	v_exp_f32_e32 v62, v62
	v_exp_f32_e32 v63, v63
	v_add_f32_e32 v60, 1.0, v60
	v_add_f32_e32 v61, 1.0, v61
	v_add_f32_e32 v62, 1.0, v62
	v_add_f32_e32 v63, 1.0, v63
	v_rcp_f32_e32 v60, v60
	v_rcp_f32_e32 v61, v61
	v_rcp_f32_e32 v62, v62
	v_rcp_f32_e32 v63, v63
	v_mul_f32_e32 v6, v6, v56
	v_mul_f32_e32 v7, v7, v57
	v_mul_f32_e32 v8, v8, v58
	v_mul_f32_e32 v9, v9, v59
	v_mul_f32_e32 v6, v6, v60
	v_mul_f32_e32 v7, v7, v61
	v_mul_f32_e32 v8, v8, v62
	v_mul_f32_e32 v9, v9, v63
	v_cvt_pk_bf16_f32 v66, v6, v7
	v_cvt_pk_bf16_f32 v67, v8, v9
	global_store_dwordx2 v[36:37], v[66:67], off offset:80
	s_waitcnt vmcnt(7)
	v_lshlrev_b32_e32 v56, 16, v52
	v_and_b32_e32 v57, 0xffff0000, v52
	v_lshlrev_b32_e32 v58, 16, v53
	v_and_b32_e32 v59, 0xffff0000, v53
	v_mul_f32_e32 v60, 0xbfb8aa3b, v56
	v_mul_f32_e32 v61, 0xbfb8aa3b, v57
	v_mul_f32_e32 v62, 0xbfb8aa3b, v58
	v_mul_f32_e32 v63, 0xbfb8aa3b, v59
	v_exp_f32_e32 v60, v60
	v_exp_f32_e32 v61, v61
	v_exp_f32_e32 v62, v62
	v_exp_f32_e32 v63, v63
	v_add_f32_e32 v60, 1.0, v60
	v_add_f32_e32 v61, 1.0, v61
	v_add_f32_e32 v62, 1.0, v62
	v_add_f32_e32 v63, 1.0, v63
	v_rcp_f32_e32 v60, v60
	v_rcp_f32_e32 v61, v61
	v_rcp_f32_e32 v62, v62
	v_rcp_f32_e32 v63, v63
	v_mul_f32_e32 v10, v10, v56
	v_mul_f32_e32 v11, v11, v57
	v_mul_f32_e32 v12, v12, v58
	v_mul_f32_e32 v13, v13, v59
	v_mul_f32_e32 v10, v10, v60
	v_mul_f32_e32 v11, v11, v61
	v_mul_f32_e32 v12, v12, v62
	v_mul_f32_e32 v13, v13, v63
	v_cvt_pk_bf16_f32 v64, v10, v11
	v_cvt_pk_bf16_f32 v65, v12, v13
	global_store_dwordx2 v[36:37], v[64:65], off offset:96
	s_waitcnt vmcnt(7)
	v_lshlrev_b32_e32 v56, 16, v54
	v_and_b32_e32 v57, 0xffff0000, v54
	v_lshlrev_b32_e32 v58, 16, v55
	v_and_b32_e32 v59, 0xffff0000, v55
	v_mul_f32_e32 v60, 0xbfb8aa3b, v56
	v_mul_f32_e32 v61, 0xbfb8aa3b, v57
	v_mul_f32_e32 v62, 0xbfb8aa3b, v58
	v_mul_f32_e32 v63, 0xbfb8aa3b, v59
	v_exp_f32_e32 v60, v60
	v_exp_f32_e32 v61, v61
	v_exp_f32_e32 v62, v62
	v_exp_f32_e32 v63, v63
	v_add_f32_e32 v60, 1.0, v60
	v_add_f32_e32 v61, 1.0, v61
	v_add_f32_e32 v62, 1.0, v62
	v_add_f32_e32 v63, 1.0, v63
	v_rcp_f32_e32 v60, v60
	v_rcp_f32_e32 v61, v61
	v_rcp_f32_e32 v62, v62
	v_rcp_f32_e32 v63, v63
	v_mul_f32_e32 v14, v14, v56
	v_mul_f32_e32 v15, v15, v57
	v_mul_f32_e32 v16, v16, v58
	v_mul_f32_e32 v17, v17, v59
	v_mul_f32_e32 v14, v14, v60
	v_mul_f32_e32 v15, v15, v61
	v_mul_f32_e32 v16, v16, v62
	v_mul_f32_e32 v17, v17, v63
	v_cvt_pk_bf16_f32 v66, v14, v15
	v_cvt_pk_bf16_f32 v67, v16, v17
	global_store_dwordx2 v[36:37], v[66:67], off offset:112
	v_readlane_b32 s0, v255, 33
	s_nop 0
	s_add_i32 s29, s29, s0
	s_cmpk_gt_i32 s29, 0xff
	s_cbranch_scc1 .LBB0_203

; #define BLO(u) __uint_as_float((u) << 16)
; #define BHI(u) __uint_as_float((u) & 0xffff0000u)
; DI int otid() { int t; asm volatile("v_mov_b32 %0, %1" : "=v"(t) : "v"((int)threadIdx.x)); __builtin_assume(t >= 0 && t < 256); return t; }
; DI void mla_item(const Params& p, int l, int item, char* smem) {
;     ...
;     const int it = item - 1792, tid = otid();
; #pragma unroll 1
;     for (int rep = 0; rep < 3; ++rep) {
;       const int u = rep * 256 + tid, tl = u / 6, slot = u - tl * 6;
;       const size_t t = (size_t)it * 128 + tl; const int pos = (int)(t & (SEQ - 1));
;       bf16_t* hp = P_PROJ + t * PW + (slot < 4 ? C_BQ + slot * 64 : C_BK + (slot - 4) * 64);
;       const float* g = (slot < 4 ? p.gq_g : p.gk_g) + l * 64;
;       uint4 q[8];
; #pragma unroll
;       for (int c = 0; c < 8; ++c) q[c] = *(const uint4*)(hp + c * 8);
;       float ss = 0.f;
; #pragma unroll
;       for (int c = 0; c < 8; ++c) {
;         float f;
;         f = BLO(q[c].x); ss += f * f; f = BHI(q[c].x); ss += f * f; f = BLO(q[c].y); ss += f * f; f = BHI(q[c].y); ss += f * f;
;         f = BLO(q[c].z); ss += f * f; f = BHI(q[c].z); ss += f * f; f = BLO(q[c].w); ss += f * f; f = BHI(q[c].w); ss += f * f;
;       }
;       float sc = rsqrtf(ss * (1.0f / 64.0f) + 1e-6f);
;       if (slot < 4) sc *= QS64;
.LBB0_210:
	v_mov_b32 v154, v188
	v_mov_b32 v0, v188
	s_cmpk_gt_i32 s27, 0x2ff
	v_lshrrev_b32_e32 v155, 7, v0
	v_bfe_u32 v152, v0, 6, 1
	v_and_b32_e32 v156, 15, v154
	v_lshrrev_b32_e32 v153, 4, v154
	s_mov_b64 s[0:1], -1
	s_cbranch_scc0 .LBB0_221
	s_cmpk_gt_u32 s27, 0x6ff
	s_cbranch_scc0 .LBB0_217
	s_add_i32 s0, s27, 0xfffff900
	s_lshl_b32 s22, s0, 7
	v_readlane_b32 s12, v255, 3
	v_readlane_b32 s13, v255, 4
	s_movk_i32 s4, 0x2600
	v_mov_b32_e32 v150, v188
	v_mul_hi_u32 v151, v150, s33
	v_lshrrev_b32_e32 v151, 2, v151
	v_mul_u32_u24_e32 v157, 6, v151
	v_sub_u32_e32 v157, v150, v157
	v_add_u32_e32 v170, s22, v151
	v_mul_lo_u32 v171, v170, s4
	v_lshl_add_u32 v171, v157, 7, v171
	global_load_dwordx4 v[2:5], v171, s[12:13] offset:0
	global_load_dwordx4 v[6:9], v171, s[12:13] offset:16
	global_load_dwordx4 v[10:13], v171, s[12:13] offset:32
	global_load_dwordx4 v[14:17], v171, s[12:13] offset:48
	global_load_dwordx4 v[18:21], v171, s[12:13] offset:64
	global_load_dwordx4 v[22:25], v171, s[12:13] offset:80
	global_load_dwordx4 v[26:29], v171, s[12:13] offset:96
	global_load_dwordx4 v[30:33], v171, s[12:13] offset:112
	v_lshlrev_b32_e32 v172, 1, v170
	v_and_b32_e32 v172, 0x3f80, v172
	v_and_b32_e32 v173, 63, v170
	v_lshlrev_b32_e32 v173, 7, v173
	global_load_dwordx4 v[34:37], v172, s[88:89] offset:0
	global_load_dwordx4 v[38:41], v172, s[88:89] offset:16
	global_load_dwordx4 v[42:45], v172, s[88:89] offset:32
	global_load_dwordx4 v[46:49], v172, s[88:89] offset:48
	global_load_dwordx4 v[50:53], v172, s[88:89] offset:64
	global_load_dwordx4 v[54:57], v172, s[88:89] offset:80
	global_load_dwordx4 v[58:61], v172, s[88:89] offset:96
	global_load_dwordx4 v[62:65], v172, s[88:89] offset:112
	global_load_dwordx4 v[66:69], v173, s[88:89] offset:0
	global_load_dwordx4 v[70:73], v173, s[88:89] offset:16
	global_load_dwordx4 v[74:77], v173, s[88:89] offset:32
	global_load_dwordx4 v[78:81], v173, s[88:89] offset:48
	global_load_dwordx4 v[82:85], v173, s[88:89] offset:64
	global_load_dwordx4 v[86:89], v173, s[88:89] offset:80
	global_load_dwordx4 v[90:93], v173, s[88:89] offset:96
	global_load_dwordx4 v[94:97], v173, s[88:89] offset:112
	v_cmp_gt_u32_e32 vcc, 4, v157
	v_mov_b32_e32 v176, s44
	v_mov_b32_e32 v177, s74
	v_cndmask_b32_e32 v184, v176, v177, vcc
	v_mov_b32_e32 v176, s45
	v_mov_b32_e32 v177, s75
	v_cndmask_b32_e32 v185, v176, v177, vcc
	v_lshl_add_u64 v[184:185], v[184:185], 0, s[94:95]
	v_mov_b32_e32 v176, 1.0
	v_mov_b32_e32 v177, 0x3e38aa3b
	v_cndmask_b32_e32 v183, v176, v177, vcc
	global_load_dwordx4 v[98:101], v[184:185], off offset:0
	global_load_dwordx4 v[102:105], v[184:185], off offset:16
	global_load_dwordx4 v[106:109], v[184:185], off offset:32
	global_load_dwordx4 v[110:113], v[184:185], off offset:48
	global_load_dwordx4 v[114:117], v[184:185], off offset:64
	global_load_dwordx4 v[118:121], v[184:185], off offset:80
	global_load_dwordx4 v[122:125], v[184:185], off offset:96
	global_load_dwordx4 v[126:129], v[184:185], off offset:112
	global_load_dwordx4 v[130:133], v[184:185], off offset:128
	global_load_dwordx4 v[134:137], v[184:185], off offset:144
	global_load_dwordx4 v[138:141], v[184:185], off offset:160
	global_load_dwordx4 v[142:145], v[184:185], off offset:176
	global_load_dwordx4 v[146:149], v[184:185], off offset:192
	global_load_dwordx4 v[158:161], v[184:185], off offset:208
	global_load_dwordx4 v[162:165], v[184:185], off offset:224
	global_load_dwordx4 v[166:169], v[184:185], off offset:240
	s_waitcnt vmcnt(32)
	v_mov_b32_e32 v174, 0
	v_lshlrev_b32_e32 v176, 16, v2
	v_and_b32_e32 v177, 0xffff0000, v2
	v_fmac_f32_e32 v174, v176, v176
	v_fmac_f32_e32 v174, v177, v177
	v_lshlrev_b32_e32 v176, 16, v3
	v_and_b32_e32 v177, 0xffff0000, v3
	v_fmac_f32_e32 v174, v176, v176
	v_fmac_f32_e32 v174, v177, v177
	v_lshlrev_b32_e32 v176, 16, v4
	v_and_b32_e32 v177, 0xffff0000, v4
	v_fmac_f32_e32 v174, v176, v176
	v_fmac_f32_e32 v174, v177, v177
	v_lshlrev_b32_e32 v176, 16, v5
	v_and_b32_e32 v177, 0xffff0000, v5
	v_fmac_f32_e32 v174, v176, v176
	v_fmac_f32_e32 v174, v177, v177
	v_lshlrev_b32_e32 v176, 16, v6
	v_and_b32_e32 v177, 0xffff0000, v6
	v_fmac_f32_e32 v174, v176, v176
	v_fmac_f32_e32 v174, v177, v177
	v_lshlrev_b32_e32 v176, 16, v7
	v_and_b32_e32 v177, 0xffff0000, v7
	v_fmac_f32_e32 v174, v176, v176
	v_fmac_f32_e32 v174, v177, v177
	v_lshlrev_b32_e32 v176, 16, v8
	v_and_b32_e32 v177, 0xffff0000, v8
	v_fmac_f32_e32 v174, v176, v176
	v_fmac_f32_e32 v174, v177, v177
	v_lshlrev_b32_e32 v176, 16, v9
	v_and_b32_e32 v177, 0xffff0000, v9
	v_fmac_f32_e32 v174, v176, v176
	v_fmac_f32_e32 v174, v177, v177
	v_lshlrev_b32_e32 v176, 16, v10
	v_and_b32_e32 v177, 0xffff0000, v10
	v_fmac_f32_e32 v174, v176, v176
	v_fmac_f32_e32 v174, v177, v177
	v_lshlrev_b32_e32 v176, 16, v11
	v_and_b32_e32 v177, 0xffff0000, v11
	v_fmac_f32_e32 v174, v176, v176
	v_fmac_f32_e32 v174, v177, v177
	v_lshlrev_b32_e32 v176, 16, v12
	v_and_b32_e32 v177, 0xffff0000, v12
	v_fmac_f32_e32 v174, v176, v176
	v_fmac_f32_e32 v174, v177, v177
	v_lshlrev_b32_e32 v176, 16, v13
	v_and_b32_e32 v177, 0xffff0000, v13
	v_fmac_f32_e32 v174, v176, v176
	v_fmac_f32_e32 v174, v177, v177
	v_lshlrev_b32_e32 v176, 16, v14
	v_and_b32_e32 v177, 0xffff0000, v14
	v_fmac_f32_e32 v174, v176, v176
	v_fmac_f32_e32 v174, v177, v177
	v_lshlrev_b32_e32 v176, 16, v15
	v_and_b32_e32 v177, 0xffff0000, v15
	v_fmac_f32_e32 v174, v176, v176
	v_fmac_f32_e32 v174, v177, v177
	v_lshlrev_b32_e32 v176, 16, v16
	v_and_b32_e32 v177, 0xffff0000, v16
	v_fmac_f32_e32 v174, v176, v176
	v_fmac_f32_e32 v174, v177, v177
	v_lshlrev_b32_e32 v176, 16, v17
	v_and_b32_e32 v177, 0xffff0000, v17
	v_fmac_f32_e32 v174, v176, v176
; #define P_ROPE WSP(float, OFF_ROPE)
; DI unsigned pack2(float a, float b) { f2_t v = {a, b}; bf2_t r = __builtin_convertvector(v, bf2_t); return __builtin_bit_cast(unsigned, r); }
; #define BLO(u) __uint_as_float((u) << 16)
; DI void mla_item(const Params& p, int l, int item, char* smem) {
;     ...
;       for (int c = 0; c < 8; ++c) {
;         float f;
;         f = BLO(q[c].x); ss += f * f; f = BHI(q[c].x); ss += f * f; f = BLO(q[c].y); ss += f * f; f = BHI(q[c].y); ss += f * f;
;         f = BLO(q[c].z); ss += f * f; f = BHI(q[c].z); ss += f * f; f = BLO(q[c].w); ss += f * f; f = BHI(q[c].w); ss += f * f;
;       }
;       float sc = rsqrtf(ss * (1.0f / 64.0f) + 1e-6f);
;       if (slot < 4) sc *= QS64;
; #pragma unroll
;       for (int pi = 0; pi < 4; ++pi) {
;         const int c = (pi & 1) + (pi >> 1) * 4;
;         const float* tab = P_ROPE + ((pi >> 1) ? (pos & 63) : (pos >> 6)) * 32 + (pi & 1) * 8;
;         const float4 c0 = *(const float4*)(tab), c1 = *(const float4*)(tab + 4), s0 = *(const float4*)(tab + 16), s1 = *(const float4*)(tab + 20);
;         const float cs[8] = {c0.x, c0.y, c0.z, c0.w, c1.x, c1.y, c1.z, c1.w}, sn[8] = {s0.x, s0.y, s0.z, s0.w, s1.x, s1.y, s1.z, s1.w};
;         const float4 ga0 = *(const float4*)(g + c * 8), ga1 = *(const float4*)(g + c * 8 + 4), gb0 = *(const float4*)(g + c * 8 + 16), gb1 = *(const float4*)(g + c * 8 + 20);
;         const float ga[8] = {ga0.x, ga0.y, ga0.z, ga0.w, ga1.x, ga1.y, ga1.z, ga1.w}, gb[8] = {gb0.x, gb0.y, gb0.z, gb0.w, gb1.x, gb1.y, gb1.z, gb1.w};
;         const unsigned ua[4] = {q[c].x, q[c].y, q[c].z, q[c].w}, ub[4] = {q[c + 2].x, q[c + 2].y, q[c + 2].z, q[c + 2].w};
;         unsigned oa[4], ob[4];
; #pragma unroll
;         for (int e = 0; e < 4; ++e) {
;           const float x1l = BLO(ua[e]) * sc * ga[2 * e], x1h = BHI(ua[e]) * sc * ga[2 * e + 1];
;           const float x2l = BLO(ub[e]) * sc * gb[2 * e], x2h = BHI(ub[e]) * sc * gb[2 * e + 1];
;           oa[e] = pack2(x1l * cs[2 * e] - x2l * sn[2 * e], x1h * cs[2 * e + 1] - x2h * sn[2 * e + 1]);
;           ob[e] = pack2(x1l * sn[2 * e] + x2l * cs[2 * e], x1h * sn[2 * e + 1] + x2h * cs[2 * e + 1]);
;         }
;         uint4 wa, wb; wa.x = oa[0]; wa.y = oa[1]; wa.z = oa[2]; wa.w = oa[3]; wb.x = ob[0]; wb.y = ob[1]; wb.z = ob[2]; wb.w = ob[3];
;         *(uint4*)(hp + c * 8) = wa; *(uint4*)(hp + (c + 2) * 8) = wb;
;       }
	v_fmac_f32_e32 v174, v177, v177
	v_lshlrev_b32_e32 v176, 16, v18
	v_and_b32_e32 v177, 0xffff0000, v18
	v_fmac_f32_e32 v174, v176, v176
	v_fmac_f32_e32 v174, v177, v177
	v_lshlrev_b32_e32 v176, 16, v19
	v_and_b32_e32 v177, 0xffff0000, v19
	v_fmac_f32_e32 v174, v176, v176
	v_fmac_f32_e32 v174, v177, v177
	v_lshlrev_b32_e32 v176, 16, v20
	v_and_b32_e32 v177, 0xffff0000, v20
	v_fmac_f32_e32 v174, v176, v176
	v_fmac_f32_e32 v174, v177, v177
	v_lshlrev_b32_e32 v176, 16, v21
	v_and_b32_e32 v177, 0xffff0000, v21
	v_fmac_f32_e32 v174, v176, v176
	v_fmac_f32_e32 v174, v177, v177
	v_lshlrev_b32_e32 v176, 16, v22
	v_and_b32_e32 v177, 0xffff0000, v22
	v_fmac_f32_e32 v174, v176, v176
	v_fmac_f32_e32 v174, v177, v177
	v_lshlrev_b32_e32 v176, 16, v23
	v_and_b32_e32 v177, 0xffff0000, v23
	v_fmac_f32_e32 v174, v176, v176
	v_fmac_f32_e32 v174, v177, v177
	v_lshlrev_b32_e32 v176, 16, v24
	v_and_b32_e32 v177, 0xffff0000, v24
	v_fmac_f32_e32 v174, v176, v176
	v_fmac_f32_e32 v174, v177, v177
	v_lshlrev_b32_e32 v176, 16, v25
	v_and_b32_e32 v177, 0xffff0000, v25
	v_fmac_f32_e32 v174, v176, v176
	v_fmac_f32_e32 v174, v177, v177
	v_lshlrev_b32_e32 v176, 16, v26
	v_and_b32_e32 v177, 0xffff0000, v26
	v_fmac_f32_e32 v174, v176, v176
	v_fmac_f32_e32 v174, v177, v177
	v_lshlrev_b32_e32 v176, 16, v27
	v_and_b32_e32 v177, 0xffff0000, v27
	v_fmac_f32_e32 v174, v176, v176
	v_fmac_f32_e32 v174, v177, v177
	v_lshlrev_b32_e32 v176, 16, v28
	v_and_b32_e32 v177, 0xffff0000, v28
	v_fmac_f32_e32 v174, v176, v176
	v_fmac_f32_e32 v174, v177, v177
	v_lshlrev_b32_e32 v176, 16, v29
	v_and_b32_e32 v177, 0xffff0000, v29
	v_fmac_f32_e32 v174, v176, v176
	v_fmac_f32_e32 v174, v177, v177
	v_lshlrev_b32_e32 v176, 16, v30
	v_and_b32_e32 v177, 0xffff0000, v30
	v_fmac_f32_e32 v174, v176, v176
	v_fmac_f32_e32 v174, v177, v177
	v_lshlrev_b32_e32 v176, 16, v31
	v_and_b32_e32 v177, 0xffff0000, v31
	v_fmac_f32_e32 v174, v176, v176
	v_fmac_f32_e32 v174, v177, v177
	v_lshlrev_b32_e32 v176, 16, v32
	v_and_b32_e32 v177, 0xffff0000, v32
	v_fmac_f32_e32 v174, v176, v176
	v_fmac_f32_e32 v174, v177, v177
	v_lshlrev_b32_e32 v176, 16, v33
	v_and_b32_e32 v177, 0xffff0000, v33
	v_fmac_f32_e32 v174, v176, v176
	v_fmac_f32_e32 v174, v177, v177
	v_mov_b32_e32 v176, 0x3c800000
	v_fma_f32 v174, v174, v176, v190
	v_rsq_f32_e32 v175, v174
	s_nop 0
	v_mul_f32_e32 v175, v175, v183
	s_waitcnt vmcnt(0)
	v_lshlrev_b32_e32 v178, 16, v2
	v_lshlrev_b32_e32 v179, 16, v10
	v_mul_f32_e32 v178, v178, v175
	v_mul_f32_e32 v179, v179, v175
	v_mul_f32_e32 v178, v178, v98
	v_mul_f32_e32 v179, v179, v114
	v_mul_f32_e32 v176, v179, v50
	v_fma_f32 v180, v178, v34, -v176
	v_mul_f32_e32 v176, v179, v34
	v_fma_f32 v181, v178, v50, v176
	v_and_b32_e32 v178, 0xffff0000, v2
	v_and_b32_e32 v179, 0xffff0000, v10
	v_mul_f32_e32 v178, v178, v175
	v_mul_f32_e32 v179, v179, v175
	v_mul_f32_e32 v178, v178, v99
	v_mul_f32_e32 v179, v179, v115
	v_mul_f32_e32 v176, v179, v51
	v_fma_f32 v182, v178, v35, -v176
	v_mul_f32_e32 v176, v179, v35
	v_fma_f32 v177, v178, v51, v176
	v_cvt_pk_bf16_f32 v2, v180, v182
	v_cvt_pk_bf16_f32 v10, v181, v177
	v_lshlrev_b32_e32 v178, 16, v3
	v_lshlrev_b32_e32 v179, 16, v11
	v_mul_f32_e32 v178, v178, v175
	v_mul_f32_e32 v179, v179, v175
	v_mul_f32_e32 v178, v178, v100
	v_mul_f32_e32 v179, v179, v116
	v_mul_f32_e32 v176, v179, v52
	v_fma_f32 v180, v178, v36, -v176
	v_mul_f32_e32 v176, v179, v36
	v_fma_f32 v181, v178, v52, v176
	v_and_b32_e32 v178, 0xffff0000, v3
	v_and_b32_e32 v179, 0xffff0000, v11
	v_mul_f32_e32 v178, v178, v175
	v_mul_f32_e32 v179, v179, v175
	v_mul_f32_e32 v178, v178, v101
	v_mul_f32_e32 v179, v179, v117
	v_mul_f32_e32 v176, v179, v53
	v_fma_f32 v182, v178, v37, -v176
	v_mul_f32_e32 v176, v179, v37
	v_fma_f32 v177, v178, v53, v176
	v_cvt_pk_bf16_f32 v3, v180, v182
	v_cvt_pk_bf16_f32 v11, v181, v177
	v_lshlrev_b32_e32 v178, 16, v4
	v_lshlrev_b32_e32 v179, 16, v12
	v_mul_f32_e32 v178, v178, v175
	v_mul_f32_e32 v179, v179, v175
	v_mul_f32_e32 v178, v178, v102
	v_mul_f32_e32 v179, v179, v118
	v_mul_f32_e32 v176, v179, v54
	v_fma_f32 v180, v178, v38, -v176
	v_mul_f32_e32 v176, v179, v38
	v_fma_f32 v181, v178, v54, v176
	v_and_b32_e32 v178, 0xffff0000, v4
	v_and_b32_e32 v179, 0xffff0000, v12
	v_mul_f32_e32 v178, v178, v175
	v_mul_f32_e32 v179, v179, v175
	v_mul_f32_e32 v178, v178, v103
	v_mul_f32_e32 v179, v179, v119
	v_mul_f32_e32 v176, v179, v55
	v_fma_f32 v182, v178, v39, -v176
	v_mul_f32_e32 v176, v179, v39
	v_fma_f32 v177, v178, v55, v176
	v_cvt_pk_bf16_f32 v4, v180, v182
	v_cvt_pk_bf16_f32 v12, v181, v177
	v_lshlrev_b32_e32 v178, 16, v5
	v_lshlrev_b32_e32 v179, 16, v13
	v_mul_f32_e32 v178, v178, v175
	v_mul_f32_e32 v179, v179, v175
	v_mul_f32_e32 v178, v178, v104
	v_mul_f32_e32 v179, v179, v120
	v_mul_f32_e32 v176, v179, v56
	v_fma_f32 v180, v178, v40, -v176
	v_mul_f32_e32 v176, v179, v40
	v_fma_f32 v181, v178, v56, v176
	v_and_b32_e32 v178, 0xffff0000, v5
	v_and_b32_e32 v179, 0xffff0000, v13
	v_mul_f32_e32 v178, v178, v175
	v_mul_f32_e32 v179, v179, v175
	v_mul_f32_e32 v178, v178, v105
	v_mul_f32_e32 v179, v179, v121
	v_mul_f32_e32 v176, v179, v57
	v_fma_f32 v182, v178, v41, -v176
	v_mul_f32_e32 v176, v179, v41
	v_fma_f32 v177, v178, v57, v176
	v_cvt_pk_bf16_f32 v5, v180, v182
	v_cvt_pk_bf16_f32 v13, v181, v177
	global_store_dwordx4 v171, v[2:5], s[12:13] offset:0
	global_store_dwordx4 v171, v[10:13], s[12:13] offset:32
	v_lshlrev_b32_e32 v178, 16, v6
	v_lshlrev_b32_e32 v179, 16, v14
	v_mul_f32_e32 v178, v178, v175
	v_mul_f32_e32 v179, v179, v175
	v_mul_f32_e32 v178, v178, v106
	v_mul_f32_e32 v179, v179, v122
	v_mul_f32_e32 v176, v179, v58
	v_fma_f32 v180, v178, v42, -v176
	v_mul_f32_e32 v176, v179, v42
; #define P_ROPE WSP(float, OFF_ROPE)
; DI unsigned pack2(float a, float b) { f2_t v = {a, b}; bf2_t r = __builtin_convertvector(v, bf2_t); return __builtin_bit_cast(unsigned, r); }
; #define BLO(u) __uint_as_float((u) << 16)
; #define BHI(u) __uint_as_float((u) & 0xffff0000u)
; DI void mla_item(const Params& p, int l, int item, char* smem) {
;     ...
;       for (int pi = 0; pi < 4; ++pi) {
;         const int c = (pi & 1) + (pi >> 1) * 4;
;         const float* tab = P_ROPE + ((pi >> 1) ? (pos & 63) : (pos >> 6)) * 32 + (pi & 1) * 8;
;         const float4 c0 = *(const float4*)(tab), c1 = *(const float4*)(tab + 4), s0 = *(const float4*)(tab + 16), s1 = *(const float4*)(tab + 20);
;         const float cs[8] = {c0.x, c0.y, c0.z, c0.w, c1.x, c1.y, c1.z, c1.w}, sn[8] = {s0.x, s0.y, s0.z, s0.w, s1.x, s1.y, s1.z, s1.w};
;         const float4 ga0 = *(const float4*)(g + c * 8), ga1 = *(const float4*)(g + c * 8 + 4), gb0 = *(const float4*)(g + c * 8 + 16), gb1 = *(const float4*)(g + c * 8 + 20);
;         const float ga[8] = {ga0.x, ga0.y, ga0.z, ga0.w, ga1.x, ga1.y, ga1.z, ga1.w}, gb[8] = {gb0.x, gb0.y, gb0.z, gb0.w, gb1.x, gb1.y, gb1.z, gb1.w};
;         const unsigned ua[4] = {q[c].x, q[c].y, q[c].z, q[c].w}, ub[4] = {q[c + 2].x, q[c + 2].y, q[c + 2].z, q[c + 2].w};
;         unsigned oa[4], ob[4];
; #pragma unroll
;         for (int e = 0; e < 4; ++e) {
;           const float x1l = BLO(ua[e]) * sc * ga[2 * e], x1h = BHI(ua[e]) * sc * ga[2 * e + 1];
;           const float x2l = BLO(ub[e]) * sc * gb[2 * e], x2h = BHI(ub[e]) * sc * gb[2 * e + 1];
;           oa[e] = pack2(x1l * cs[2 * e] - x2l * sn[2 * e], x1h * cs[2 * e + 1] - x2h * sn[2 * e + 1]);
;           ob[e] = pack2(x1l * sn[2 * e] + x2l * cs[2 * e], x1h * sn[2 * e + 1] + x2h * cs[2 * e + 1]);
;         }
;         uint4 wa, wb; wa.x = oa[0]; wa.y = oa[1]; wa.z = oa[2]; wa.w = oa[3]; wb.x = ob[0]; wb.y = ob[1]; wb.z = ob[2]; wb.w = ob[3];
;         *(uint4*)(hp + c * 8) = wa; *(uint4*)(hp + (c + 2) * 8) = wb;
;       }
	v_fma_f32 v181, v178, v58, v176
	v_and_b32_e32 v178, 0xffff0000, v6
	v_and_b32_e32 v179, 0xffff0000, v14
	v_mul_f32_e32 v178, v178, v175
	v_mul_f32_e32 v179, v179, v175
	v_mul_f32_e32 v178, v178, v107
	v_mul_f32_e32 v179, v179, v123
	v_mul_f32_e32 v176, v179, v59
	v_fma_f32 v182, v178, v43, -v176
	v_mul_f32_e32 v176, v179, v43
	v_fma_f32 v177, v178, v59, v176
	v_cvt_pk_bf16_f32 v6, v180, v182
	v_cvt_pk_bf16_f32 v14, v181, v177
	v_lshlrev_b32_e32 v178, 16, v7
	v_lshlrev_b32_e32 v179, 16, v15
	v_mul_f32_e32 v178, v178, v175
	v_mul_f32_e32 v179, v179, v175
	v_mul_f32_e32 v178, v178, v108
	v_mul_f32_e32 v179, v179, v124
	v_mul_f32_e32 v176, v179, v60
	v_fma_f32 v180, v178, v44, -v176
	v_mul_f32_e32 v176, v179, v44
	v_fma_f32 v181, v178, v60, v176
	v_and_b32_e32 v178, 0xffff0000, v7
	v_and_b32_e32 v179, 0xffff0000, v15
	v_mul_f32_e32 v178, v178, v175
	v_mul_f32_e32 v179, v179, v175
	v_mul_f32_e32 v178, v178, v109
	v_mul_f32_e32 v179, v179, v125
	v_mul_f32_e32 v176, v179, v61
	v_fma_f32 v182, v178, v45, -v176
	v_mul_f32_e32 v176, v179, v45
	v_fma_f32 v177, v178, v61, v176
	v_cvt_pk_bf16_f32 v7, v180, v182
	v_cvt_pk_bf16_f32 v15, v181, v177
	v_lshlrev_b32_e32 v178, 16, v8
	v_lshlrev_b32_e32 v179, 16, v16
	v_mul_f32_e32 v178, v178, v175
	v_mul_f32_e32 v179, v179, v175
	v_mul_f32_e32 v178, v178, v110
	v_mul_f32_e32 v179, v179, v126
	v_mul_f32_e32 v176, v179, v62
	v_fma_f32 v180, v178, v46, -v176
	v_mul_f32_e32 v176, v179, v46
	v_fma_f32 v181, v178, v62, v176
	v_and_b32_e32 v178, 0xffff0000, v8
	v_and_b32_e32 v179, 0xffff0000, v16
	v_mul_f32_e32 v178, v178, v175
	v_mul_f32_e32 v179, v179, v175
	v_mul_f32_e32 v178, v178, v111
	v_mul_f32_e32 v179, v179, v127
	v_mul_f32_e32 v176, v179, v63
	v_fma_f32 v182, v178, v47, -v176
	v_mul_f32_e32 v176, v179, v47
	v_fma_f32 v177, v178, v63, v176
	v_cvt_pk_bf16_f32 v8, v180, v182
	v_cvt_pk_bf16_f32 v16, v181, v177
	v_lshlrev_b32_e32 v178, 16, v9
	v_lshlrev_b32_e32 v179, 16, v17
	v_mul_f32_e32 v178, v178, v175
	v_mul_f32_e32 v179, v179, v175
	v_mul_f32_e32 v178, v178, v112
	v_mul_f32_e32 v179, v179, v128
	v_mul_f32_e32 v176, v179, v64
	v_fma_f32 v180, v178, v48, -v176
	v_mul_f32_e32 v176, v179, v48
	v_fma_f32 v181, v178, v64, v176
	v_and_b32_e32 v178, 0xffff0000, v9
	v_and_b32_e32 v179, 0xffff0000, v17
	v_mul_f32_e32 v178, v178, v175
	v_mul_f32_e32 v179, v179, v175
	v_mul_f32_e32 v178, v178, v113
	v_mul_f32_e32 v179, v179, v129
	v_mul_f32_e32 v176, v179, v65
	v_fma_f32 v182, v178, v49, -v176
	v_mul_f32_e32 v176, v179, v49
	v_fma_f32 v177, v178, v65, v176
	v_cvt_pk_bf16_f32 v9, v180, v182
	v_cvt_pk_bf16_f32 v17, v181, v177
	global_store_dwordx4 v171, v[6:9], s[12:13] offset:16
	global_store_dwordx4 v171, v[14:17], s[12:13] offset:48
	v_lshlrev_b32_e32 v178, 16, v18
	v_lshlrev_b32_e32 v179, 16, v26
	v_mul_f32_e32 v178, v178, v175
	v_mul_f32_e32 v179, v179, v175
	v_mul_f32_e32 v178, v178, v130
	v_mul_f32_e32 v179, v179, v146
	v_mul_f32_e32 v176, v179, v82
	v_fma_f32 v180, v178, v66, -v176
	v_mul_f32_e32 v176, v179, v66
	v_fma_f32 v181, v178, v82, v176
	v_and_b32_e32 v178, 0xffff0000, v18
	v_and_b32_e32 v179, 0xffff0000, v26
	v_mul_f32_e32 v178, v178, v175
	v_mul_f32_e32 v179, v179, v175
	v_mul_f32_e32 v178, v178, v131
	v_mul_f32_e32 v179, v179, v147
	v_mul_f32_e32 v176, v179, v83
	v_fma_f32 v182, v178, v67, -v176
	v_mul_f32_e32 v176, v179, v67
	v_fma_f32 v177, v178, v83, v176
	v_cvt_pk_bf16_f32 v18, v180, v182
	v_cvt_pk_bf16_f32 v26, v181, v177
	v_lshlrev_b32_e32 v178, 16, v19
	v_lshlrev_b32_e32 v179, 16, v27
	v_mul_f32_e32 v178, v178, v175
	v_mul_f32_e32 v179, v179, v175
	v_mul_f32_e32 v178, v178, v132
	v_mul_f32_e32 v179, v179, v148
	v_mul_f32_e32 v176, v179, v84
	v_fma_f32 v180, v178, v68, -v176
	v_mul_f32_e32 v176, v179, v68
	v_fma_f32 v181, v178, v84, v176
	v_and_b32_e32 v178, 0xffff0000, v19
	v_and_b32_e32 v179, 0xffff0000, v27
	v_mul_f32_e32 v178, v178, v175
	v_mul_f32_e32 v179, v179, v175
	v_mul_f32_e32 v178, v178, v133
	v_mul_f32_e32 v179, v179, v149
	v_mul_f32_e32 v176, v179, v85
	v_fma_f32 v182, v178, v69, -v176
	v_mul_f32_e32 v176, v179, v69
	v_fma_f32 v177, v178, v85, v176
	v_cvt_pk_bf16_f32 v19, v180, v182
	v_cvt_pk_bf16_f32 v27, v181, v177
	v_lshlrev_b32_e32 v178, 16, v20
	v_lshlrev_b32_e32 v179, 16, v28
	v_mul_f32_e32 v178, v178, v175
	v_mul_f32_e32 v179, v179, v175
	v_mul_f32_e32 v178, v178, v134
	v_mul_f32_e32 v179, v179, v158
	v_mul_f32_e32 v176, v179, v86
	v_fma_f32 v180, v178, v70, -v176
	v_mul_f32_e32 v176, v179, v70
	v_fma_f32 v181, v178, v86, v176
	v_and_b32_e32 v178, 0xffff0000, v20
	v_and_b32_e32 v179, 0xffff0000, v28
	v_mul_f32_e32 v178, v178, v175
	v_mul_f32_e32 v179, v179, v175
	v_mul_f32_e32 v178, v178, v135
	v_mul_f32_e32 v179, v179, v159
	v_mul_f32_e32 v176, v179, v87
	v_fma_f32 v182, v178, v71, -v176
	v_mul_f32_e32 v176, v179, v71
	v_fma_f32 v177, v178, v87, v176
	v_cvt_pk_bf16_f32 v20, v180, v182
	v_cvt_pk_bf16_f32 v28, v181, v177
	v_lshlrev_b32_e32 v178, 16, v21
	v_lshlrev_b32_e32 v179, 16, v29
	v_mul_f32_e32 v178, v178, v175
	v_mul_f32_e32 v179, v179, v175
	v_mul_f32_e32 v178, v178, v136
	v_mul_f32_e32 v179, v179, v160
	v_mul_f32_e32 v176, v179, v88
	v_fma_f32 v180, v178, v72, -v176
	v_mul_f32_e32 v176, v179, v72
	v_fma_f32 v181, v178, v88, v176
	v_and_b32_e32 v178, 0xffff0000, v21
	v_and_b32_e32 v179, 0xffff0000, v29
	v_mul_f32_e32 v178, v178, v175
	v_mul_f32_e32 v179, v179, v175
	v_mul_f32_e32 v178, v178, v137
	v_mul_f32_e32 v179, v179, v161
	v_mul_f32_e32 v176, v179, v89
	v_fma_f32 v182, v178, v73, -v176
	v_mul_f32_e32 v176, v179, v73
	v_fma_f32 v177, v178, v89, v176
	v_cvt_pk_bf16_f32 v21, v180, v182
	v_cvt_pk_bf16_f32 v29, v181, v177
	global_store_dwordx4 v171, v[18:21], s[12:13] offset:64
; #define P_ROPE WSP(float, OFF_ROPE)
; DI unsigned pack2(float a, float b) { f2_t v = {a, b}; bf2_t r = __builtin_convertvector(v, bf2_t); return __builtin_bit_cast(unsigned, r); }
; #define BLO(u) __uint_as_float((u) << 16)
; DI void mla_item(const Params& p, int l, int item, char* smem) {
;     ...
;       const int u = rep * 256 + tid, tl = u / 6, slot = u - tl * 6;
;       const size_t t = (size_t)it * 128 + tl; const int pos = (int)(t & (SEQ - 1));
;       bf16_t* hp = P_PROJ + t * PW + (slot < 4 ? C_BQ + slot * 64 : C_BK + (slot - 4) * 64);
;       const float* g = (slot < 4 ? p.gq_g : p.gk_g) + l * 64;
;       uint4 q[8];
; #pragma unroll
;       for (int c = 0; c < 8; ++c) q[c] = *(const uint4*)(hp + c * 8);
;     ...
;       for (int pi = 0; pi < 4; ++pi) {
;         const int c = (pi & 1) + (pi >> 1) * 4;
;         const float* tab = P_ROPE + ((pi >> 1) ? (pos & 63) : (pos >> 6)) * 32 + (pi & 1) * 8;
;         const float4 c0 = *(const float4*)(tab), c1 = *(const float4*)(tab + 4), s0 = *(const float4*)(tab + 16), s1 = *(const float4*)(tab + 20);
;         const float cs[8] = {c0.x, c0.y, c0.z, c0.w, c1.x, c1.y, c1.z, c1.w}, sn[8] = {s0.x, s0.y, s0.z, s0.w, s1.x, s1.y, s1.z, s1.w};
;         const float4 ga0 = *(const float4*)(g + c * 8), ga1 = *(const float4*)(g + c * 8 + 4), gb0 = *(const float4*)(g + c * 8 + 16), gb1 = *(const float4*)(g + c * 8 + 20);
;         const float ga[8] = {ga0.x, ga0.y, ga0.z, ga0.w, ga1.x, ga1.y, ga1.z, ga1.w}, gb[8] = {gb0.x, gb0.y, gb0.z, gb0.w, gb1.x, gb1.y, gb1.z, gb1.w};
;         const unsigned ua[4] = {q[c].x, q[c].y, q[c].z, q[c].w}, ub[4] = {q[c + 2].x, q[c + 2].y, q[c + 2].z, q[c + 2].w};
;         unsigned oa[4], ob[4];
; #pragma unroll
;         for (int e = 0; e < 4; ++e) {
;           const float x1l = BLO(ua[e]) * sc * ga[2 * e], x1h = BHI(ua[e]) * sc * ga[2 * e + 1];
;           const float x2l = BLO(ub[e]) * sc * gb[2 * e], x2h = BHI(ub[e]) * sc * gb[2 * e + 1];
;           oa[e] = pack2(x1l * cs[2 * e] - x2l * sn[2 * e], x1h * cs[2 * e + 1] - x2h * sn[2 * e + 1]);
;           ob[e] = pack2(x1l * sn[2 * e] + x2l * cs[2 * e], x1h * sn[2 * e + 1] + x2h * cs[2 * e + 1]);
;         }
;         uint4 wa, wb; wa.x = oa[0]; wa.y = oa[1]; wa.z = oa[2]; wa.w = oa[3]; wb.x = ob[0]; wb.y = ob[1]; wb.z = ob[2]; wb.w = ob[3];
;         *(uint4*)(hp + c * 8) = wa; *(uint4*)(hp + (c + 2) * 8) = wb;
;       }
	global_store_dwordx4 v171, v[26:29], s[12:13] offset:96
	v_lshlrev_b32_e32 v178, 16, v22
	v_lshlrev_b32_e32 v179, 16, v30
	v_mul_f32_e32 v178, v178, v175
	v_mul_f32_e32 v179, v179, v175
	v_mul_f32_e32 v178, v178, v138
	v_mul_f32_e32 v179, v179, v162
	v_mul_f32_e32 v176, v179, v90
	v_fma_f32 v180, v178, v74, -v176
	v_mul_f32_e32 v176, v179, v74
	v_fma_f32 v181, v178, v90, v176
	v_and_b32_e32 v178, 0xffff0000, v22
	v_and_b32_e32 v179, 0xffff0000, v30
	v_mul_f32_e32 v178, v178, v175
	v_mul_f32_e32 v179, v179, v175
	v_mul_f32_e32 v178, v178, v139
	v_mul_f32_e32 v179, v179, v163
	v_mul_f32_e32 v176, v179, v91
	v_fma_f32 v182, v178, v75, -v176
	v_mul_f32_e32 v176, v179, v75
	v_fma_f32 v177, v178, v91, v176
	v_cvt_pk_bf16_f32 v22, v180, v182
	v_cvt_pk_bf16_f32 v30, v181, v177
	v_lshlrev_b32_e32 v178, 16, v23
	v_lshlrev_b32_e32 v179, 16, v31
	v_mul_f32_e32 v178, v178, v175
	v_mul_f32_e32 v179, v179, v175
	v_mul_f32_e32 v178, v178, v140
	v_mul_f32_e32 v179, v179, v164
	v_mul_f32_e32 v176, v179, v92
	v_fma_f32 v180, v178, v76, -v176
	v_mul_f32_e32 v176, v179, v76
	v_fma_f32 v181, v178, v92, v176
	v_and_b32_e32 v178, 0xffff0000, v23
	v_and_b32_e32 v179, 0xffff0000, v31
	v_mul_f32_e32 v178, v178, v175
	v_mul_f32_e32 v179, v179, v175
	v_mul_f32_e32 v178, v178, v141
	v_mul_f32_e32 v179, v179, v165
	v_mul_f32_e32 v176, v179, v93
	v_fma_f32 v182, v178, v77, -v176
	v_mul_f32_e32 v176, v179, v77
	v_fma_f32 v177, v178, v93, v176
	v_cvt_pk_bf16_f32 v23, v180, v182
	v_cvt_pk_bf16_f32 v31, v181, v177
	v_lshlrev_b32_e32 v178, 16, v24
	v_lshlrev_b32_e32 v179, 16, v32
	v_mul_f32_e32 v178, v178, v175
	v_mul_f32_e32 v179, v179, v175
	v_mul_f32_e32 v178, v178, v142
	v_mul_f32_e32 v179, v179, v166
	v_mul_f32_e32 v176, v179, v94
	v_fma_f32 v180, v178, v78, -v176
	v_mul_f32_e32 v176, v179, v78
	v_fma_f32 v181, v178, v94, v176
	v_and_b32_e32 v178, 0xffff0000, v24
	v_and_b32_e32 v179, 0xffff0000, v32
	v_mul_f32_e32 v178, v178, v175
	v_mul_f32_e32 v179, v179, v175
	v_mul_f32_e32 v178, v178, v143
	v_mul_f32_e32 v179, v179, v167
	v_mul_f32_e32 v176, v179, v95
	v_fma_f32 v182, v178, v79, -v176
	v_mul_f32_e32 v176, v179, v79
	v_fma_f32 v177, v178, v95, v176
	v_cvt_pk_bf16_f32 v24, v180, v182
	v_cvt_pk_bf16_f32 v32, v181, v177
	v_lshlrev_b32_e32 v178, 16, v25
	v_lshlrev_b32_e32 v179, 16, v33
	v_mul_f32_e32 v178, v178, v175
	v_mul_f32_e32 v179, v179, v175
	v_mul_f32_e32 v178, v178, v144
	v_mul_f32_e32 v179, v179, v168
	v_mul_f32_e32 v176, v179, v96
	v_fma_f32 v180, v178, v80, -v176
	v_mul_f32_e32 v176, v179, v80
	v_fma_f32 v181, v178, v96, v176
	v_and_b32_e32 v178, 0xffff0000, v25
	v_and_b32_e32 v179, 0xffff0000, v33
	v_mul_f32_e32 v178, v178, v175
	v_mul_f32_e32 v179, v179, v175
	v_mul_f32_e32 v178, v178, v145
	v_mul_f32_e32 v179, v179, v169
	v_mul_f32_e32 v176, v179, v97
	v_fma_f32 v182, v178, v81, -v176
	v_mul_f32_e32 v176, v179, v81
	v_fma_f32 v177, v178, v97, v176
	v_cvt_pk_bf16_f32 v25, v180, v182
	v_cvt_pk_bf16_f32 v33, v181, v177
	global_store_dwordx4 v171, v[22:25], s[12:13] offset:80
	global_store_dwordx4 v171, v[30:33], s[12:13] offset:112
	s_nop 1
	v_add_u32_e32 v150, 0x100, v188
	v_mul_hi_u32 v151, v150, s33
	v_lshrrev_b32_e32 v151, 2, v151
	v_mul_u32_u24_e32 v157, 6, v151
	v_sub_u32_e32 v157, v150, v157
	v_add_u32_e32 v170, s22, v151
	v_mul_lo_u32 v171, v170, s4
	v_lshl_add_u32 v171, v157, 7, v171
	global_load_dwordx4 v[2:5], v171, s[12:13] offset:0
	global_load_dwordx4 v[6:9], v171, s[12:13] offset:16
	global_load_dwordx4 v[10:13], v171, s[12:13] offset:32
	global_load_dwordx4 v[14:17], v171, s[12:13] offset:48
	global_load_dwordx4 v[18:21], v171, s[12:13] offset:64
	global_load_dwordx4 v[22:25], v171, s[12:13] offset:80
	global_load_dwordx4 v[26:29], v171, s[12:13] offset:96
	global_load_dwordx4 v[30:33], v171, s[12:13] offset:112
	v_lshlrev_b32_e32 v172, 1, v170
	v_and_b32_e32 v172, 0x3f80, v172
	v_and_b32_e32 v173, 63, v170
	v_lshlrev_b32_e32 v173, 7, v173
	global_load_dwordx4 v[34:37], v172, s[88:89] offset:0
	global_load_dwordx4 v[38:41], v172, s[88:89] offset:16
	global_load_dwordx4 v[42:45], v172, s[88:89] offset:32
	global_load_dwordx4 v[46:49], v172, s[88:89] offset:48
	global_load_dwordx4 v[50:53], v172, s[88:89] offset:64
	global_load_dwordx4 v[54:57], v172, s[88:89] offset:80
	global_load_dwordx4 v[58:61], v172, s[88:89] offset:96
	global_load_dwordx4 v[62:65], v172, s[88:89] offset:112
	global_load_dwordx4 v[66:69], v173, s[88:89] offset:0
	global_load_dwordx4 v[70:73], v173, s[88:89] offset:16
	global_load_dwordx4 v[74:77], v173, s[88:89] offset:32
	global_load_dwordx4 v[78:81], v173, s[88:89] offset:48
	global_load_dwordx4 v[82:85], v173, s[88:89] offset:64
	global_load_dwordx4 v[86:89], v173, s[88:89] offset:80
	global_load_dwordx4 v[90:93], v173, s[88:89] offset:96
	global_load_dwordx4 v[94:97], v173, s[88:89] offset:112
	v_cmp_gt_u32_e32 vcc, 4, v157
	v_mov_b32_e32 v176, s44
	v_mov_b32_e32 v177, s74
	v_cndmask_b32_e32 v184, v176, v177, vcc
	v_mov_b32_e32 v176, s45
	v_mov_b32_e32 v177, s75
	v_cndmask_b32_e32 v185, v176, v177, vcc
	v_lshl_add_u64 v[184:185], v[184:185], 0, s[94:95]
	v_mov_b32_e32 v176, 1.0
	v_mov_b32_e32 v177, 0x3e38aa3b
	v_cndmask_b32_e32 v183, v176, v177, vcc
	global_load_dwordx4 v[98:101], v[184:185], off offset:0
	global_load_dwordx4 v[102:105], v[184:185], off offset:16
	global_load_dwordx4 v[106:109], v[184:185], off offset:32
	global_load_dwordx4 v[110:113], v[184:185], off offset:48
	global_load_dwordx4 v[114:117], v[184:185], off offset:64
	global_load_dwordx4 v[118:121], v[184:185], off offset:80
	global_load_dwordx4 v[122:125], v[184:185], off offset:96
	global_load_dwordx4 v[126:129], v[184:185], off offset:112
	global_load_dwordx4 v[130:133], v[184:185], off offset:128
	global_load_dwordx4 v[134:137], v[184:185], off offset:144
	global_load_dwordx4 v[138:141], v[184:185], off offset:160
	global_load_dwordx4 v[142:145], v[184:185], off offset:176
	global_load_dwordx4 v[146:149], v[184:185], off offset:192
	global_load_dwordx4 v[158:161], v[184:185], off offset:208
	global_load_dwordx4 v[162:165], v[184:185], off offset:224
	global_load_dwordx4 v[166:169], v[184:185], off offset:240
	s_waitcnt vmcnt(32)
; #define BLO(u) __uint_as_float((u) << 16)
; #define BHI(u) __uint_as_float((u) & 0xffff0000u)
; DI void mla_item(const Params& p, int l, int item, char* smem) {
;     ...
; #pragma unroll
;       for (int c = 0; c < 8; ++c) {
;         float f;
;         f = BLO(q[c].x); ss += f * f; f = BHI(q[c].x); ss += f * f; f = BLO(q[c].y); ss += f * f; f = BHI(q[c].y); ss += f * f;
;         f = BLO(q[c].z); ss += f * f; f = BHI(q[c].z); ss += f * f; f = BLO(q[c].w); ss += f * f; f = BHI(q[c].w); ss += f * f;
;       }
;       float sc = rsqrtf(ss * (1.0f / 64.0f) + 1e-6f);
;       if (slot < 4) sc *= QS64;
	v_mov_b32_e32 v174, 0
	v_lshlrev_b32_e32 v176, 16, v2
	v_and_b32_e32 v177, 0xffff0000, v2
	v_fmac_f32_e32 v174, v176, v176
	v_fmac_f32_e32 v174, v177, v177
	v_lshlrev_b32_e32 v176, 16, v3
	v_and_b32_e32 v177, 0xffff0000, v3
	v_fmac_f32_e32 v174, v176, v176
	v_fmac_f32_e32 v174, v177, v177
	v_lshlrev_b32_e32 v176, 16, v4
	v_and_b32_e32 v177, 0xffff0000, v4
	v_fmac_f32_e32 v174, v176, v176
	v_fmac_f32_e32 v174, v177, v177
	v_lshlrev_b32_e32 v176, 16, v5
	v_and_b32_e32 v177, 0xffff0000, v5
	v_fmac_f32_e32 v174, v176, v176
	v_fmac_f32_e32 v174, v177, v177
	v_lshlrev_b32_e32 v176, 16, v6
	v_and_b32_e32 v177, 0xffff0000, v6
	v_fmac_f32_e32 v174, v176, v176
	v_fmac_f32_e32 v174, v177, v177
	v_lshlrev_b32_e32 v176, 16, v7
	v_and_b32_e32 v177, 0xffff0000, v7
	v_fmac_f32_e32 v174, v176, v176
	v_fmac_f32_e32 v174, v177, v177
	v_lshlrev_b32_e32 v176, 16, v8
	v_and_b32_e32 v177, 0xffff0000, v8
	v_fmac_f32_e32 v174, v176, v176
	v_fmac_f32_e32 v174, v177, v177
	v_lshlrev_b32_e32 v176, 16, v9
	v_and_b32_e32 v177, 0xffff0000, v9
	v_fmac_f32_e32 v174, v176, v176
	v_fmac_f32_e32 v174, v177, v177
	v_lshlrev_b32_e32 v176, 16, v10
	v_and_b32_e32 v177, 0xffff0000, v10
	v_fmac_f32_e32 v174, v176, v176
	v_fmac_f32_e32 v174, v177, v177
	v_lshlrev_b32_e32 v176, 16, v11
	v_and_b32_e32 v177, 0xffff0000, v11
	v_fmac_f32_e32 v174, v176, v176
	v_fmac_f32_e32 v174, v177, v177
	v_lshlrev_b32_e32 v176, 16, v12
	v_and_b32_e32 v177, 0xffff0000, v12
	v_fmac_f32_e32 v174, v176, v176
	v_fmac_f32_e32 v174, v177, v177
	v_lshlrev_b32_e32 v176, 16, v13
	v_and_b32_e32 v177, 0xffff0000, v13
	v_fmac_f32_e32 v174, v176, v176
	v_fmac_f32_e32 v174, v177, v177
	v_lshlrev_b32_e32 v176, 16, v14
	v_and_b32_e32 v177, 0xffff0000, v14
	v_fmac_f32_e32 v174, v176, v176
	v_fmac_f32_e32 v174, v177, v177
	v_lshlrev_b32_e32 v176, 16, v15
	v_and_b32_e32 v177, 0xffff0000, v15
	v_fmac_f32_e32 v174, v176, v176
	v_fmac_f32_e32 v174, v177, v177
	v_lshlrev_b32_e32 v176, 16, v16
	v_and_b32_e32 v177, 0xffff0000, v16
	v_fmac_f32_e32 v174, v176, v176
	v_fmac_f32_e32 v174, v177, v177
	v_lshlrev_b32_e32 v176, 16, v17
	v_and_b32_e32 v177, 0xffff0000, v17
	v_fmac_f32_e32 v174, v176, v176
	v_fmac_f32_e32 v174, v177, v177
	v_lshlrev_b32_e32 v176, 16, v18
	v_and_b32_e32 v177, 0xffff0000, v18
	v_fmac_f32_e32 v174, v176, v176
	v_fmac_f32_e32 v174, v177, v177
	v_lshlrev_b32_e32 v176, 16, v19
	v_and_b32_e32 v177, 0xffff0000, v19
	v_fmac_f32_e32 v174, v176, v176
	v_fmac_f32_e32 v174, v177, v177
	v_lshlrev_b32_e32 v176, 16, v20
	v_and_b32_e32 v177, 0xffff0000, v20
	v_fmac_f32_e32 v174, v176, v176
	v_fmac_f32_e32 v174, v177, v177
	v_lshlrev_b32_e32 v176, 16, v21
	v_and_b32_e32 v177, 0xffff0000, v21
	v_fmac_f32_e32 v174, v176, v176
	v_fmac_f32_e32 v174, v177, v177
	v_lshlrev_b32_e32 v176, 16, v22
	v_and_b32_e32 v177, 0xffff0000, v22
	v_fmac_f32_e32 v174, v176, v176
	v_fmac_f32_e32 v174, v177, v177
	v_lshlrev_b32_e32 v176, 16, v23
	v_and_b32_e32 v177, 0xffff0000, v23
	v_fmac_f32_e32 v174, v176, v176
	v_fmac_f32_e32 v174, v177, v177
	v_lshlrev_b32_e32 v176, 16, v24
	v_and_b32_e32 v177, 0xffff0000, v24
	v_fmac_f32_e32 v174, v176, v176
	v_fmac_f32_e32 v174, v177, v177
	v_lshlrev_b32_e32 v176, 16, v25
	v_and_b32_e32 v177, 0xffff0000, v25
	v_fmac_f32_e32 v174, v176, v176
	v_fmac_f32_e32 v174, v177, v177
	v_lshlrev_b32_e32 v176, 16, v26
	v_and_b32_e32 v177, 0xffff0000, v26
	v_fmac_f32_e32 v174, v176, v176
	v_fmac_f32_e32 v174, v177, v177
	v_lshlrev_b32_e32 v176, 16, v27
	v_and_b32_e32 v177, 0xffff0000, v27
	v_fmac_f32_e32 v174, v176, v176
	v_fmac_f32_e32 v174, v177, v177
	v_lshlrev_b32_e32 v176, 16, v28
	v_and_b32_e32 v177, 0xffff0000, v28
	v_fmac_f32_e32 v174, v176, v176
	v_fmac_f32_e32 v174, v177, v177
	v_lshlrev_b32_e32 v176, 16, v29
	v_and_b32_e32 v177, 0xffff0000, v29
	v_fmac_f32_e32 v174, v176, v176
	v_fmac_f32_e32 v174, v177, v177
	v_lshlrev_b32_e32 v176, 16, v30
	v_and_b32_e32 v177, 0xffff0000, v30
	v_fmac_f32_e32 v174, v176, v176
	v_fmac_f32_e32 v174, v177, v177
	v_lshlrev_b32_e32 v176, 16, v31
	v_and_b32_e32 v177, 0xffff0000, v31
	v_fmac_f32_e32 v174, v176, v176
	v_fmac_f32_e32 v174, v177, v177
	v_lshlrev_b32_e32 v176, 16, v32
	v_and_b32_e32 v177, 0xffff0000, v32
	v_fmac_f32_e32 v174, v176, v176
	v_fmac_f32_e32 v174, v177, v177
	v_lshlrev_b32_e32 v176, 16, v33
	v_and_b32_e32 v177, 0xffff0000, v33
	v_fmac_f32_e32 v174, v176, v176
	v_fmac_f32_e32 v174, v177, v177
	v_mov_b32_e32 v176, 0x3c800000
	v_fma_f32 v174, v174, v176, v190
	v_rsq_f32_e32 v175, v174
	s_nop 0
	v_mul_f32_e32 v175, v175, v183
	s_waitcnt vmcnt(0)
; #define P_ROPE WSP(float, OFF_ROPE)
; DI unsigned pack2(float a, float b) { f2_t v = {a, b}; bf2_t r = __builtin_convertvector(v, bf2_t); return __builtin_bit_cast(unsigned, r); }
; #define BLO(u) __uint_as_float((u) << 16)
; #define BHI(u) __uint_as_float((u) & 0xffff0000u)
; DI void mla_item(const Params& p, int l, int item, char* smem) {
;     ...
;       for (int pi = 0; pi < 4; ++pi) {
;         const int c = (pi & 1) + (pi >> 1) * 4;
;         const float* tab = P_ROPE + ((pi >> 1) ? (pos & 63) : (pos >> 6)) * 32 + (pi & 1) * 8;
;         const float4 c0 = *(const float4*)(tab), c1 = *(const float4*)(tab + 4), s0 = *(const float4*)(tab + 16), s1 = *(const float4*)(tab + 20);
;         const float cs[8] = {c0.x, c0.y, c0.z, c0.w, c1.x, c1.y, c1.z, c1.w}, sn[8] = {s0.x, s0.y, s0.z, s0.w, s1.x, s1.y, s1.z, s1.w};
;         const float4 ga0 = *(const float4*)(g + c * 8), ga1 = *(const float4*)(g + c * 8 + 4), gb0 = *(const float4*)(g + c * 8 + 16), gb1 = *(const float4*)(g + c * 8 + 20);
;         const float ga[8] = {ga0.x, ga0.y, ga0.z, ga0.w, ga1.x, ga1.y, ga1.z, ga1.w}, gb[8] = {gb0.x, gb0.y, gb0.z, gb0.w, gb1.x, gb1.y, gb1.z, gb1.w};
;         const unsigned ua[4] = {q[c].x, q[c].y, q[c].z, q[c].w}, ub[4] = {q[c + 2].x, q[c + 2].y, q[c + 2].z, q[c + 2].w};
;         unsigned oa[4], ob[4];
; #pragma unroll
;         for (int e = 0; e < 4; ++e) {
;           const float x1l = BLO(ua[e]) * sc * ga[2 * e], x1h = BHI(ua[e]) * sc * ga[2 * e + 1];
;           const float x2l = BLO(ub[e]) * sc * gb[2 * e], x2h = BHI(ub[e]) * sc * gb[2 * e + 1];
;           oa[e] = pack2(x1l * cs[2 * e] - x2l * sn[2 * e], x1h * cs[2 * e + 1] - x2h * sn[2 * e + 1]);
;           ob[e] = pack2(x1l * sn[2 * e] + x2l * cs[2 * e], x1h * sn[2 * e + 1] + x2h * cs[2 * e + 1]);
;         }
;         uint4 wa, wb; wa.x = oa[0]; wa.y = oa[1]; wa.z = oa[2]; wa.w = oa[3]; wb.x = ob[0]; wb.y = ob[1]; wb.z = ob[2]; wb.w = ob[3];
;         *(uint4*)(hp + c * 8) = wa; *(uint4*)(hp + (c + 2) * 8) = wb;
;       }
	v_lshlrev_b32_e32 v178, 16, v2
	v_lshlrev_b32_e32 v179, 16, v10
	v_mul_f32_e32 v178, v178, v175
	v_mul_f32_e32 v179, v179, v175
	v_mul_f32_e32 v178, v178, v98
	v_mul_f32_e32 v179, v179, v114
	v_mul_f32_e32 v176, v179, v50
	v_fma_f32 v180, v178, v34, -v176
	v_mul_f32_e32 v176, v179, v34
	v_fma_f32 v181, v178, v50, v176
	v_and_b32_e32 v178, 0xffff0000, v2
	v_and_b32_e32 v179, 0xffff0000, v10
	v_mul_f32_e32 v178, v178, v175
	v_mul_f32_e32 v179, v179, v175
	v_mul_f32_e32 v178, v178, v99
	v_mul_f32_e32 v179, v179, v115
	v_mul_f32_e32 v176, v179, v51
	v_fma_f32 v182, v178, v35, -v176
	v_mul_f32_e32 v176, v179, v35
	v_fma_f32 v177, v178, v51, v176
	v_cvt_pk_bf16_f32 v2, v180, v182
	v_cvt_pk_bf16_f32 v10, v181, v177
	v_lshlrev_b32_e32 v178, 16, v3
	v_lshlrev_b32_e32 v179, 16, v11
	v_mul_f32_e32 v178, v178, v175
	v_mul_f32_e32 v179, v179, v175
	v_mul_f32_e32 v178, v178, v100
	v_mul_f32_e32 v179, v179, v116
	v_mul_f32_e32 v176, v179, v52
	v_fma_f32 v180, v178, v36, -v176
	v_mul_f32_e32 v176, v179, v36
	v_fma_f32 v181, v178, v52, v176
	v_and_b32_e32 v178, 0xffff0000, v3
	v_and_b32_e32 v179, 0xffff0000, v11
	v_mul_f32_e32 v178, v178, v175
	v_mul_f32_e32 v179, v179, v175
	v_mul_f32_e32 v178, v178, v101
	v_mul_f32_e32 v179, v179, v117
	v_mul_f32_e32 v176, v179, v53
	v_fma_f32 v182, v178, v37, -v176
	v_mul_f32_e32 v176, v179, v37
	v_fma_f32 v177, v178, v53, v176
	v_cvt_pk_bf16_f32 v3, v180, v182
	v_cvt_pk_bf16_f32 v11, v181, v177
	v_lshlrev_b32_e32 v178, 16, v4
	v_lshlrev_b32_e32 v179, 16, v12
	v_mul_f32_e32 v178, v178, v175
	v_mul_f32_e32 v179, v179, v175
	v_mul_f32_e32 v178, v178, v102
	v_mul_f32_e32 v179, v179, v118
	v_mul_f32_e32 v176, v179, v54
	v_fma_f32 v180, v178, v38, -v176
	v_mul_f32_e32 v176, v179, v38
	v_fma_f32 v181, v178, v54, v176
	v_and_b32_e32 v178, 0xffff0000, v4
	v_and_b32_e32 v179, 0xffff0000, v12
	v_mul_f32_e32 v178, v178, v175
	v_mul_f32_e32 v179, v179, v175
	v_mul_f32_e32 v178, v178, v103
	v_mul_f32_e32 v179, v179, v119
	v_mul_f32_e32 v176, v179, v55
	v_fma_f32 v182, v178, v39, -v176
	v_mul_f32_e32 v176, v179, v39
	v_fma_f32 v177, v178, v55, v176
	v_cvt_pk_bf16_f32 v4, v180, v182
	v_cvt_pk_bf16_f32 v12, v181, v177
	v_lshlrev_b32_e32 v178, 16, v5
	v_lshlrev_b32_e32 v179, 16, v13
	v_mul_f32_e32 v178, v178, v175
	v_mul_f32_e32 v179, v179, v175
	v_mul_f32_e32 v178, v178, v104
	v_mul_f32_e32 v179, v179, v120
	v_mul_f32_e32 v176, v179, v56
	v_fma_f32 v180, v178, v40, -v176
	v_mul_f32_e32 v176, v179, v40
	v_fma_f32 v181, v178, v56, v176
	v_and_b32_e32 v178, 0xffff0000, v5
	v_and_b32_e32 v179, 0xffff0000, v13
	v_mul_f32_e32 v178, v178, v175
	v_mul_f32_e32 v179, v179, v175
	v_mul_f32_e32 v178, v178, v105
	v_mul_f32_e32 v179, v179, v121
	v_mul_f32_e32 v176, v179, v57
	v_fma_f32 v182, v178, v41, -v176
	v_mul_f32_e32 v176, v179, v41
	v_fma_f32 v177, v178, v57, v176
	v_cvt_pk_bf16_f32 v5, v180, v182
	v_cvt_pk_bf16_f32 v13, v181, v177
	global_store_dwordx4 v171, v[2:5], s[12:13] offset:0
	global_store_dwordx4 v171, v[10:13], s[12:13] offset:32
	v_lshlrev_b32_e32 v178, 16, v6
	v_lshlrev_b32_e32 v179, 16, v14
	v_mul_f32_e32 v178, v178, v175
	v_mul_f32_e32 v179, v179, v175
	v_mul_f32_e32 v178, v178, v106
	v_mul_f32_e32 v179, v179, v122
	v_mul_f32_e32 v176, v179, v58
	v_fma_f32 v180, v178, v42, -v176
	v_mul_f32_e32 v176, v179, v42
	v_fma_f32 v181, v178, v58, v176
	v_and_b32_e32 v178, 0xffff0000, v6
	v_and_b32_e32 v179, 0xffff0000, v14
	v_mul_f32_e32 v178, v178, v175
	v_mul_f32_e32 v179, v179, v175
	v_mul_f32_e32 v178, v178, v107
	v_mul_f32_e32 v179, v179, v123
	v_mul_f32_e32 v176, v179, v59
	v_fma_f32 v182, v178, v43, -v176
	v_mul_f32_e32 v176, v179, v43
	v_fma_f32 v177, v178, v59, v176
	v_cvt_pk_bf16_f32 v6, v180, v182
	v_cvt_pk_bf16_f32 v14, v181, v177
	v_lshlrev_b32_e32 v178, 16, v7
	v_lshlrev_b32_e32 v179, 16, v15
	v_mul_f32_e32 v178, v178, v175
	v_mul_f32_e32 v179, v179, v175
	v_mul_f32_e32 v178, v178, v108
	v_mul_f32_e32 v179, v179, v124
	v_mul_f32_e32 v176, v179, v60
	v_fma_f32 v180, v178, v44, -v176
	v_mul_f32_e32 v176, v179, v44
	v_fma_f32 v181, v178, v60, v176
	v_and_b32_e32 v178, 0xffff0000, v7
	v_and_b32_e32 v179, 0xffff0000, v15
	v_mul_f32_e32 v178, v178, v175
	v_mul_f32_e32 v179, v179, v175
	v_mul_f32_e32 v178, v178, v109
	v_mul_f32_e32 v179, v179, v125
	v_mul_f32_e32 v176, v179, v61
	v_fma_f32 v182, v178, v45, -v176
	v_mul_f32_e32 v176, v179, v45
	v_fma_f32 v177, v178, v61, v176
	v_cvt_pk_bf16_f32 v7, v180, v182
	v_cvt_pk_bf16_f32 v15, v181, v177
	v_lshlrev_b32_e32 v178, 16, v8
	v_lshlrev_b32_e32 v179, 16, v16
	v_mul_f32_e32 v178, v178, v175
	v_mul_f32_e32 v179, v179, v175
	v_mul_f32_e32 v178, v178, v110
	v_mul_f32_e32 v179, v179, v126
	v_mul_f32_e32 v176, v179, v62
	v_fma_f32 v180, v178, v46, -v176
	v_mul_f32_e32 v176, v179, v46
	v_fma_f32 v181, v178, v62, v176
	v_and_b32_e32 v178, 0xffff0000, v8
	v_and_b32_e32 v179, 0xffff0000, v16
	v_mul_f32_e32 v178, v178, v175
	v_mul_f32_e32 v179, v179, v175
	v_mul_f32_e32 v178, v178, v111
	v_mul_f32_e32 v179, v179, v127
	v_mul_f32_e32 v176, v179, v63
	v_fma_f32 v182, v178, v47, -v176
	v_mul_f32_e32 v176, v179, v47
	v_fma_f32 v177, v178, v63, v176
	v_cvt_pk_bf16_f32 v8, v180, v182
	v_cvt_pk_bf16_f32 v16, v181, v177
	v_lshlrev_b32_e32 v178, 16, v9
	v_lshlrev_b32_e32 v179, 16, v17
	v_mul_f32_e32 v178, v178, v175
	v_mul_f32_e32 v179, v179, v175
	v_mul_f32_e32 v178, v178, v112
	v_mul_f32_e32 v179, v179, v128
	v_mul_f32_e32 v176, v179, v64
	v_fma_f32 v180, v178, v48, -v176
	v_mul_f32_e32 v176, v179, v48
	v_fma_f32 v181, v178, v64, v176
	v_and_b32_e32 v178, 0xffff0000, v9
	v_and_b32_e32 v179, 0xffff0000, v17
	v_mul_f32_e32 v178, v178, v175
	v_mul_f32_e32 v179, v179, v175
	v_mul_f32_e32 v178, v178, v113
; #define P_ROPE WSP(float, OFF_ROPE)
; DI unsigned pack2(float a, float b) { f2_t v = {a, b}; bf2_t r = __builtin_convertvector(v, bf2_t); return __builtin_bit_cast(unsigned, r); }
; #define BLO(u) __uint_as_float((u) << 16)
; #define BHI(u) __uint_as_float((u) & 0xffff0000u)
; DI void mla_item(const Params& p, int l, int item, char* smem) {
;     ...
;       for (int pi = 0; pi < 4; ++pi) {
;         const int c = (pi & 1) + (pi >> 1) * 4;
;         const float* tab = P_ROPE + ((pi >> 1) ? (pos & 63) : (pos >> 6)) * 32 + (pi & 1) * 8;
;         const float4 c0 = *(const float4*)(tab), c1 = *(const float4*)(tab + 4), s0 = *(const float4*)(tab + 16), s1 = *(const float4*)(tab + 20);
;         const float cs[8] = {c0.x, c0.y, c0.z, c0.w, c1.x, c1.y, c1.z, c1.w}, sn[8] = {s0.x, s0.y, s0.z, s0.w, s1.x, s1.y, s1.z, s1.w};
;         const float4 ga0 = *(const float4*)(g + c * 8), ga1 = *(const float4*)(g + c * 8 + 4), gb0 = *(const float4*)(g + c * 8 + 16), gb1 = *(const float4*)(g + c * 8 + 20);
;         const float ga[8] = {ga0.x, ga0.y, ga0.z, ga0.w, ga1.x, ga1.y, ga1.z, ga1.w}, gb[8] = {gb0.x, gb0.y, gb0.z, gb0.w, gb1.x, gb1.y, gb1.z, gb1.w};
;         const unsigned ua[4] = {q[c].x, q[c].y, q[c].z, q[c].w}, ub[4] = {q[c + 2].x, q[c + 2].y, q[c + 2].z, q[c + 2].w};
;         unsigned oa[4], ob[4];
; #pragma unroll
;         for (int e = 0; e < 4; ++e) {
;           const float x1l = BLO(ua[e]) * sc * ga[2 * e], x1h = BHI(ua[e]) * sc * ga[2 * e + 1];
;           const float x2l = BLO(ub[e]) * sc * gb[2 * e], x2h = BHI(ub[e]) * sc * gb[2 * e + 1];
;           oa[e] = pack2(x1l * cs[2 * e] - x2l * sn[2 * e], x1h * cs[2 * e + 1] - x2h * sn[2 * e + 1]);
;           ob[e] = pack2(x1l * sn[2 * e] + x2l * cs[2 * e], x1h * sn[2 * e + 1] + x2h * cs[2 * e + 1]);
;         }
;         uint4 wa, wb; wa.x = oa[0]; wa.y = oa[1]; wa.z = oa[2]; wa.w = oa[3]; wb.x = ob[0]; wb.y = ob[1]; wb.z = ob[2]; wb.w = ob[3];
;         *(uint4*)(hp + c * 8) = wa; *(uint4*)(hp + (c + 2) * 8) = wb;
;       }
	v_mul_f32_e32 v179, v179, v129
	v_mul_f32_e32 v176, v179, v65
	v_fma_f32 v182, v178, v49, -v176
	v_mul_f32_e32 v176, v179, v49
	v_fma_f32 v177, v178, v65, v176
	v_cvt_pk_bf16_f32 v9, v180, v182
	v_cvt_pk_bf16_f32 v17, v181, v177
	global_store_dwordx4 v171, v[6:9], s[12:13] offset:16
	global_store_dwordx4 v171, v[14:17], s[12:13] offset:48
	v_lshlrev_b32_e32 v178, 16, v18
	v_lshlrev_b32_e32 v179, 16, v26
	v_mul_f32_e32 v178, v178, v175
	v_mul_f32_e32 v179, v179, v175
	v_mul_f32_e32 v178, v178, v130
	v_mul_f32_e32 v179, v179, v146
	v_mul_f32_e32 v176, v179, v82
	v_fma_f32 v180, v178, v66, -v176
	v_mul_f32_e32 v176, v179, v66
	v_fma_f32 v181, v178, v82, v176
	v_and_b32_e32 v178, 0xffff0000, v18
	v_and_b32_e32 v179, 0xffff0000, v26
	v_mul_f32_e32 v178, v178, v175
	v_mul_f32_e32 v179, v179, v175
	v_mul_f32_e32 v178, v178, v131
	v_mul_f32_e32 v179, v179, v147
	v_mul_f32_e32 v176, v179, v83
	v_fma_f32 v182, v178, v67, -v176
	v_mul_f32_e32 v176, v179, v67
	v_fma_f32 v177, v178, v83, v176
	v_cvt_pk_bf16_f32 v18, v180, v182
	v_cvt_pk_bf16_f32 v26, v181, v177
	v_lshlrev_b32_e32 v178, 16, v19
	v_lshlrev_b32_e32 v179, 16, v27
	v_mul_f32_e32 v178, v178, v175
	v_mul_f32_e32 v179, v179, v175
	v_mul_f32_e32 v178, v178, v132
	v_mul_f32_e32 v179, v179, v148
	v_mul_f32_e32 v176, v179, v84
	v_fma_f32 v180, v178, v68, -v176
	v_mul_f32_e32 v176, v179, v68
	v_fma_f32 v181, v178, v84, v176
	v_and_b32_e32 v178, 0xffff0000, v19
	v_and_b32_e32 v179, 0xffff0000, v27
	v_mul_f32_e32 v178, v178, v175
	v_mul_f32_e32 v179, v179, v175
	v_mul_f32_e32 v178, v178, v133
	v_mul_f32_e32 v179, v179, v149
	v_mul_f32_e32 v176, v179, v85
	v_fma_f32 v182, v178, v69, -v176
	v_mul_f32_e32 v176, v179, v69
	v_fma_f32 v177, v178, v85, v176
	v_cvt_pk_bf16_f32 v19, v180, v182
	v_cvt_pk_bf16_f32 v27, v181, v177
	v_lshlrev_b32_e32 v178, 16, v20
	v_lshlrev_b32_e32 v179, 16, v28
	v_mul_f32_e32 v178, v178, v175
	v_mul_f32_e32 v179, v179, v175
	v_mul_f32_e32 v178, v178, v134
	v_mul_f32_e32 v179, v179, v158
	v_mul_f32_e32 v176, v179, v86
	v_fma_f32 v180, v178, v70, -v176
	v_mul_f32_e32 v176, v179, v70
	v_fma_f32 v181, v178, v86, v176
	v_and_b32_e32 v178, 0xffff0000, v20
	v_and_b32_e32 v179, 0xffff0000, v28
	v_mul_f32_e32 v178, v178, v175
	v_mul_f32_e32 v179, v179, v175
	v_mul_f32_e32 v178, v178, v135
	v_mul_f32_e32 v179, v179, v159
	v_mul_f32_e32 v176, v179, v87
	v_fma_f32 v182, v178, v71, -v176
	v_mul_f32_e32 v176, v179, v71
	v_fma_f32 v177, v178, v87, v176
	v_cvt_pk_bf16_f32 v20, v180, v182
	v_cvt_pk_bf16_f32 v28, v181, v177
	v_lshlrev_b32_e32 v178, 16, v21
	v_lshlrev_b32_e32 v179, 16, v29
	v_mul_f32_e32 v178, v178, v175
	v_mul_f32_e32 v179, v179, v175
	v_mul_f32_e32 v178, v178, v136
	v_mul_f32_e32 v179, v179, v160
	v_mul_f32_e32 v176, v179, v88
	v_fma_f32 v180, v178, v72, -v176
	v_mul_f32_e32 v176, v179, v72
	v_fma_f32 v181, v178, v88, v176
	v_and_b32_e32 v178, 0xffff0000, v21
	v_and_b32_e32 v179, 0xffff0000, v29
	v_mul_f32_e32 v178, v178, v175
	v_mul_f32_e32 v179, v179, v175
	v_mul_f32_e32 v178, v178, v137
	v_mul_f32_e32 v179, v179, v161
	v_mul_f32_e32 v176, v179, v89
	v_fma_f32 v182, v178, v73, -v176
	v_mul_f32_e32 v176, v179, v73
	v_fma_f32 v177, v178, v89, v176
	v_cvt_pk_bf16_f32 v21, v180, v182
	v_cvt_pk_bf16_f32 v29, v181, v177
	global_store_dwordx4 v171, v[18:21], s[12:13] offset:64
	global_store_dwordx4 v171, v[26:29], s[12:13] offset:96
	v_lshlrev_b32_e32 v178, 16, v22
	v_lshlrev_b32_e32 v179, 16, v30
	v_mul_f32_e32 v178, v178, v175
	v_mul_f32_e32 v179, v179, v175
	v_mul_f32_e32 v178, v178, v138
	v_mul_f32_e32 v179, v179, v162
	v_mul_f32_e32 v176, v179, v90
	v_fma_f32 v180, v178, v74, -v176
	v_mul_f32_e32 v176, v179, v74
	v_fma_f32 v181, v178, v90, v176
	v_and_b32_e32 v178, 0xffff0000, v22
	v_and_b32_e32 v179, 0xffff0000, v30
	v_mul_f32_e32 v178, v178, v175
	v_mul_f32_e32 v179, v179, v175
	v_mul_f32_e32 v178, v178, v139
	v_mul_f32_e32 v179, v179, v163
	v_mul_f32_e32 v176, v179, v91
	v_fma_f32 v182, v178, v75, -v176
	v_mul_f32_e32 v176, v179, v75
	v_fma_f32 v177, v178, v91, v176
	v_cvt_pk_bf16_f32 v22, v180, v182
	v_cvt_pk_bf16_f32 v30, v181, v177
	v_lshlrev_b32_e32 v178, 16, v23
	v_lshlrev_b32_e32 v179, 16, v31
	v_mul_f32_e32 v178, v178, v175
	v_mul_f32_e32 v179, v179, v175
	v_mul_f32_e32 v178, v178, v140
	v_mul_f32_e32 v179, v179, v164
	v_mul_f32_e32 v176, v179, v92
	v_fma_f32 v180, v178, v76, -v176
	v_mul_f32_e32 v176, v179, v76
	v_fma_f32 v181, v178, v92, v176
	v_and_b32_e32 v178, 0xffff0000, v23
	v_and_b32_e32 v179, 0xffff0000, v31
	v_mul_f32_e32 v178, v178, v175
	v_mul_f32_e32 v179, v179, v175
	v_mul_f32_e32 v178, v178, v141
	v_mul_f32_e32 v179, v179, v165
	v_mul_f32_e32 v176, v179, v93
	v_fma_f32 v182, v178, v77, -v176
	v_mul_f32_e32 v176, v179, v77
	v_fma_f32 v177, v178, v93, v176
	v_cvt_pk_bf16_f32 v23, v180, v182
	v_cvt_pk_bf16_f32 v31, v181, v177
	v_lshlrev_b32_e32 v178, 16, v24
	v_lshlrev_b32_e32 v179, 16, v32
	v_mul_f32_e32 v178, v178, v175
	v_mul_f32_e32 v179, v179, v175
	v_mul_f32_e32 v178, v178, v142
	v_mul_f32_e32 v179, v179, v166
	v_mul_f32_e32 v176, v179, v94
	v_fma_f32 v180, v178, v78, -v176
	v_mul_f32_e32 v176, v179, v78
	v_fma_f32 v181, v178, v94, v176
	v_and_b32_e32 v178, 0xffff0000, v24
	v_and_b32_e32 v179, 0xffff0000, v32
	v_mul_f32_e32 v178, v178, v175
	v_mul_f32_e32 v179, v179, v175
	v_mul_f32_e32 v178, v178, v143
	v_mul_f32_e32 v179, v179, v167
	v_mul_f32_e32 v176, v179, v95
	v_fma_f32 v182, v178, v79, -v176
	v_mul_f32_e32 v176, v179, v79
	v_fma_f32 v177, v178, v95, v176
	v_cvt_pk_bf16_f32 v24, v180, v182
	v_cvt_pk_bf16_f32 v32, v181, v177
	v_lshlrev_b32_e32 v178, 16, v25
	v_lshlrev_b32_e32 v179, 16, v33
	v_mul_f32_e32 v178, v178, v175
	v_mul_f32_e32 v179, v179, v175
; DI void mla_item(const Params& p, int l, int item, char* smem) {
;     ...
;       const int u = rep * 256 + tid, tl = u / 6, slot = u - tl * 6;
;       const size_t t = (size_t)it * 128 + tl; const int pos = (int)(t & (SEQ - 1));
;       bf16_t* hp = P_PROJ + t * PW + (slot < 4 ? C_BQ + slot * 64 : C_BK + (slot - 4) * 64);
;       const float* g = (slot < 4 ? p.gq_g : p.gk_g) + l * 64;
;       uint4 q[8];
; #pragma unroll
;       for (int c = 0; c < 8; ++c) q[c] = *(const uint4*)(hp + c * 8);
;       float ss = 0.f;
; #pragma unroll
;       for (int c = 0; c < 8; ++c) {
;         float f;
;         f = BLO(q[c].x); ss += f * f; f = BHI(q[c].x); ss += f * f; f = BLO(q[c].y); ss += f * f; f = BHI(q[c].y); ss += f * f;
;     ...
;       for (int pi = 0; pi < 4; ++pi) {
;         const int c = (pi & 1) + (pi >> 1) * 4;
;         const float* tab = P_ROPE + ((pi >> 1) ? (pos & 63) : (pos >> 6)) * 32 + (pi & 1) * 8;
;         const float4 c0 = *(const float4*)(tab), c1 = *(const float4*)(tab + 4), s0 = *(const float4*)(tab + 16), s1 = *(const float4*)(tab + 20);
;         const float cs[8] = {c0.x, c0.y, c0.z, c0.w, c1.x, c1.y, c1.z, c1.w}, sn[8] = {s0.x, s0.y, s0.z, s0.w, s1.x, s1.y, s1.z, s1.w};
;         const float4 ga0 = *(const float4*)(g + c * 8), ga1 = *(const float4*)(g + c * 8 + 4), gb0 = *(const float4*)(g + c * 8 + 16), gb1 = *(const float4*)(g + c * 8 + 20);
;         const float ga[8] = {ga0.x, ga0.y, ga0.z, ga0.w, ga1.x, ga1.y, ga1.z, ga1.w}, gb[8] = {gb0.x, gb0.y, gb0.z, gb0.w, gb1.x, gb1.y, gb1.z, gb1.w};
;         const unsigned ua[4] = {q[c].x, q[c].y, q[c].z, q[c].w}, ub[4] = {q[c + 2].x, q[c + 2].y, q[c + 2].z, q[c + 2].w};
;         unsigned oa[4], ob[4];
; #pragma unroll
;         for (int e = 0; e < 4; ++e) {
;           const float x1l = BLO(ua[e]) * sc * ga[2 * e], x1h = BHI(ua[e]) * sc * ga[2 * e + 1];
;           const float x2l = BLO(ub[e]) * sc * gb[2 * e], x2h = BHI(ub[e]) * sc * gb[2 * e + 1];
;           oa[e] = pack2(x1l * cs[2 * e] - x2l * sn[2 * e], x1h * cs[2 * e + 1] - x2h * sn[2 * e + 1]);
;           ob[e] = pack2(x1l * sn[2 * e] + x2l * cs[2 * e], x1h * sn[2 * e + 1] + x2h * cs[2 * e + 1]);
;         }
;         uint4 wa, wb; wa.x = oa[0]; wa.y = oa[1]; wa.z = oa[2]; wa.w = oa[3]; wb.x = ob[0]; wb.y = ob[1]; wb.z = ob[2]; wb.w = ob[3];
;         *(uint4*)(hp + c * 8) = wa; *(uint4*)(hp + (c + 2) * 8) = wb;
;       }
	v_mul_f32_e32 v178, v178, v144
	v_mul_f32_e32 v179, v179, v168
	v_mul_f32_e32 v176, v179, v96
	v_fma_f32 v180, v178, v80, -v176
	v_mul_f32_e32 v176, v179, v80
	v_fma_f32 v181, v178, v96, v176
	v_and_b32_e32 v178, 0xffff0000, v25
	v_and_b32_e32 v179, 0xffff0000, v33
	v_mul_f32_e32 v178, v178, v175
	v_mul_f32_e32 v179, v179, v175
	v_mul_f32_e32 v178, v178, v145
	v_mul_f32_e32 v179, v179, v169
	v_mul_f32_e32 v176, v179, v97
	v_fma_f32 v182, v178, v81, -v176
	v_mul_f32_e32 v176, v179, v81
	v_fma_f32 v177, v178, v97, v176
	v_cvt_pk_bf16_f32 v25, v180, v182
	v_cvt_pk_bf16_f32 v33, v181, v177
	global_store_dwordx4 v171, v[22:25], s[12:13] offset:80
	global_store_dwordx4 v171, v[30:33], s[12:13] offset:112
	s_nop 1
	v_add_u32_e32 v150, 0x200, v188
	v_mul_hi_u32 v151, v150, s33
	v_lshrrev_b32_e32 v151, 2, v151
	v_mul_u32_u24_e32 v157, 6, v151
	v_sub_u32_e32 v157, v150, v157
	v_add_u32_e32 v170, s22, v151
	v_mul_lo_u32 v171, v170, s4
	v_lshl_add_u32 v171, v157, 7, v171
	global_load_dwordx4 v[2:5], v171, s[12:13] offset:0
	global_load_dwordx4 v[6:9], v171, s[12:13] offset:16
	global_load_dwordx4 v[10:13], v171, s[12:13] offset:32
	global_load_dwordx4 v[14:17], v171, s[12:13] offset:48
	global_load_dwordx4 v[18:21], v171, s[12:13] offset:64
	global_load_dwordx4 v[22:25], v171, s[12:13] offset:80
	global_load_dwordx4 v[26:29], v171, s[12:13] offset:96
	global_load_dwordx4 v[30:33], v171, s[12:13] offset:112
	v_lshlrev_b32_e32 v172, 1, v170
	v_and_b32_e32 v172, 0x3f80, v172
	v_and_b32_e32 v173, 63, v170
	v_lshlrev_b32_e32 v173, 7, v173
	global_load_dwordx4 v[34:37], v172, s[88:89] offset:0
	global_load_dwordx4 v[38:41], v172, s[88:89] offset:16
	global_load_dwordx4 v[42:45], v172, s[88:89] offset:32
	global_load_dwordx4 v[46:49], v172, s[88:89] offset:48
	global_load_dwordx4 v[50:53], v172, s[88:89] offset:64
	global_load_dwordx4 v[54:57], v172, s[88:89] offset:80
	global_load_dwordx4 v[58:61], v172, s[88:89] offset:96
	global_load_dwordx4 v[62:65], v172, s[88:89] offset:112
	global_load_dwordx4 v[66:69], v173, s[88:89] offset:0
	global_load_dwordx4 v[70:73], v173, s[88:89] offset:16
	global_load_dwordx4 v[74:77], v173, s[88:89] offset:32
	global_load_dwordx4 v[78:81], v173, s[88:89] offset:48
	global_load_dwordx4 v[82:85], v173, s[88:89] offset:64
	global_load_dwordx4 v[86:89], v173, s[88:89] offset:80
	global_load_dwordx4 v[90:93], v173, s[88:89] offset:96
	global_load_dwordx4 v[94:97], v173, s[88:89] offset:112
	v_cmp_gt_u32_e32 vcc, 4, v157
	v_mov_b32_e32 v176, s44
	v_mov_b32_e32 v177, s74
	v_cndmask_b32_e32 v184, v176, v177, vcc
	v_mov_b32_e32 v176, s45
	v_mov_b32_e32 v177, s75
	v_cndmask_b32_e32 v185, v176, v177, vcc
	v_lshl_add_u64 v[184:185], v[184:185], 0, s[94:95]
	v_mov_b32_e32 v176, 1.0
	v_mov_b32_e32 v177, 0x3e38aa3b
	v_cndmask_b32_e32 v183, v176, v177, vcc
	global_load_dwordx4 v[98:101], v[184:185], off offset:0
	global_load_dwordx4 v[102:105], v[184:185], off offset:16
	global_load_dwordx4 v[106:109], v[184:185], off offset:32
	global_load_dwordx4 v[110:113], v[184:185], off offset:48
	global_load_dwordx4 v[114:117], v[184:185], off offset:64
	global_load_dwordx4 v[118:121], v[184:185], off offset:80
	global_load_dwordx4 v[122:125], v[184:185], off offset:96
	global_load_dwordx4 v[126:129], v[184:185], off offset:112
	global_load_dwordx4 v[130:133], v[184:185], off offset:128
	global_load_dwordx4 v[134:137], v[184:185], off offset:144
	global_load_dwordx4 v[138:141], v[184:185], off offset:160
	global_load_dwordx4 v[142:145], v[184:185], off offset:176
	global_load_dwordx4 v[146:149], v[184:185], off offset:192
	global_load_dwordx4 v[158:161], v[184:185], off offset:208
	global_load_dwordx4 v[162:165], v[184:185], off offset:224
	global_load_dwordx4 v[166:169], v[184:185], off offset:240
	s_waitcnt vmcnt(32)
	v_mov_b32_e32 v174, 0
	v_lshlrev_b32_e32 v176, 16, v2
	v_and_b32_e32 v177, 0xffff0000, v2
	v_fmac_f32_e32 v174, v176, v176
	v_fmac_f32_e32 v174, v177, v177
	v_lshlrev_b32_e32 v176, 16, v3
	v_and_b32_e32 v177, 0xffff0000, v3
	v_fmac_f32_e32 v174, v176, v176
	v_fmac_f32_e32 v174, v177, v177
	v_lshlrev_b32_e32 v176, 16, v4
	v_and_b32_e32 v177, 0xffff0000, v4
	v_fmac_f32_e32 v174, v176, v176
	v_fmac_f32_e32 v174, v177, v177
	v_lshlrev_b32_e32 v176, 16, v5
	v_and_b32_e32 v177, 0xffff0000, v5
	v_fmac_f32_e32 v174, v176, v176
	v_fmac_f32_e32 v174, v177, v177
	v_lshlrev_b32_e32 v176, 16, v6
	v_and_b32_e32 v177, 0xffff0000, v6
	v_fmac_f32_e32 v174, v176, v176
	v_fmac_f32_e32 v174, v177, v177
	v_lshlrev_b32_e32 v176, 16, v7
	v_and_b32_e32 v177, 0xffff0000, v7
	v_fmac_f32_e32 v174, v176, v176
	v_fmac_f32_e32 v174, v177, v177
	v_lshlrev_b32_e32 v176, 16, v8
	v_and_b32_e32 v177, 0xffff0000, v8
	v_fmac_f32_e32 v174, v176, v176
	v_fmac_f32_e32 v174, v177, v177
	v_lshlrev_b32_e32 v176, 16, v9
	v_and_b32_e32 v177, 0xffff0000, v9
	v_fmac_f32_e32 v174, v176, v176
	v_fmac_f32_e32 v174, v177, v177
	v_lshlrev_b32_e32 v176, 16, v10
	v_and_b32_e32 v177, 0xffff0000, v10
	v_fmac_f32_e32 v174, v176, v176
	v_fmac_f32_e32 v174, v177, v177
	v_lshlrev_b32_e32 v176, 16, v11
	v_and_b32_e32 v177, 0xffff0000, v11
	v_fmac_f32_e32 v174, v176, v176
	v_fmac_f32_e32 v174, v177, v177
	v_lshlrev_b32_e32 v176, 16, v12
	v_and_b32_e32 v177, 0xffff0000, v12
	v_fmac_f32_e32 v174, v176, v176
	v_fmac_f32_e32 v174, v177, v177
	v_lshlrev_b32_e32 v176, 16, v13
	v_and_b32_e32 v177, 0xffff0000, v13
	v_fmac_f32_e32 v174, v176, v176
	v_fmac_f32_e32 v174, v177, v177
	v_lshlrev_b32_e32 v176, 16, v14
	v_and_b32_e32 v177, 0xffff0000, v14
	v_fmac_f32_e32 v174, v176, v176
	v_fmac_f32_e32 v174, v177, v177
	v_lshlrev_b32_e32 v176, 16, v15
	v_and_b32_e32 v177, 0xffff0000, v15
; #define P_ROPE WSP(float, OFF_ROPE)
; DI unsigned pack2(float a, float b) { f2_t v = {a, b}; bf2_t r = __builtin_convertvector(v, bf2_t); return __builtin_bit_cast(unsigned, r); }
; DI void mla_item(const Params& p, int l, int item, char* smem) {
;     ...
; #pragma unroll
;       for (int c = 0; c < 8; ++c) {
;         float f;
;         f = BLO(q[c].x); ss += f * f; f = BHI(q[c].x); ss += f * f; f = BLO(q[c].y); ss += f * f; f = BHI(q[c].y); ss += f * f;
;         f = BLO(q[c].z); ss += f * f; f = BHI(q[c].z); ss += f * f; f = BLO(q[c].w); ss += f * f; f = BHI(q[c].w); ss += f * f;
;       }
;       float sc = rsqrtf(ss * (1.0f / 64.0f) + 1e-6f);
;       if (slot < 4) sc *= QS64;
; #pragma unroll
;       for (int pi = 0; pi < 4; ++pi) {
;         const int c = (pi & 1) + (pi >> 1) * 4;
;         const float* tab = P_ROPE + ((pi >> 1) ? (pos & 63) : (pos >> 6)) * 32 + (pi & 1) * 8;
;         const float4 c0 = *(const float4*)(tab), c1 = *(const float4*)(tab + 4), s0 = *(const float4*)(tab + 16), s1 = *(const float4*)(tab + 20);
;         const float cs[8] = {c0.x, c0.y, c0.z, c0.w, c1.x, c1.y, c1.z, c1.w}, sn[8] = {s0.x, s0.y, s0.z, s0.w, s1.x, s1.y, s1.z, s1.w};
;         const float4 ga0 = *(const float4*)(g + c * 8), ga1 = *(const float4*)(g + c * 8 + 4), gb0 = *(const float4*)(g + c * 8 + 16), gb1 = *(const float4*)(g + c * 8 + 20);
;         const float ga[8] = {ga0.x, ga0.y, ga0.z, ga0.w, ga1.x, ga1.y, ga1.z, ga1.w}, gb[8] = {gb0.x, gb0.y, gb0.z, gb0.w, gb1.x, gb1.y, gb1.z, gb1.w};
;         const unsigned ua[4] = {q[c].x, q[c].y, q[c].z, q[c].w}, ub[4] = {q[c + 2].x, q[c + 2].y, q[c + 2].z, q[c + 2].w};
;         unsigned oa[4], ob[4];
; #pragma unroll
;         for (int e = 0; e < 4; ++e) {
;           const float x1l = BLO(ua[e]) * sc * ga[2 * e], x1h = BHI(ua[e]) * sc * ga[2 * e + 1];
;           const float x2l = BLO(ub[e]) * sc * gb[2 * e], x2h = BHI(ub[e]) * sc * gb[2 * e + 1];
;           oa[e] = pack2(x1l * cs[2 * e] - x2l * sn[2 * e], x1h * cs[2 * e + 1] - x2h * sn[2 * e + 1]);
;           ob[e] = pack2(x1l * sn[2 * e] + x2l * cs[2 * e], x1h * sn[2 * e + 1] + x2h * cs[2 * e + 1]);
;         }
;         uint4 wa, wb; wa.x = oa[0]; wa.y = oa[1]; wa.z = oa[2]; wa.w = oa[3]; wb.x = ob[0]; wb.y = ob[1]; wb.z = ob[2]; wb.w = ob[3];
;         *(uint4*)(hp + c * 8) = wa; *(uint4*)(hp + (c + 2) * 8) = wb;
;       }
	v_fmac_f32_e32 v174, v176, v176
	v_fmac_f32_e32 v174, v177, v177
	v_lshlrev_b32_e32 v176, 16, v16
	v_and_b32_e32 v177, 0xffff0000, v16
	v_fmac_f32_e32 v174, v176, v176
	v_fmac_f32_e32 v174, v177, v177
	v_lshlrev_b32_e32 v176, 16, v17
	v_and_b32_e32 v177, 0xffff0000, v17
	v_fmac_f32_e32 v174, v176, v176
	v_fmac_f32_e32 v174, v177, v177
	v_lshlrev_b32_e32 v176, 16, v18
	v_and_b32_e32 v177, 0xffff0000, v18
	v_fmac_f32_e32 v174, v176, v176
	v_fmac_f32_e32 v174, v177, v177
	v_lshlrev_b32_e32 v176, 16, v19
	v_and_b32_e32 v177, 0xffff0000, v19
	v_fmac_f32_e32 v174, v176, v176
	v_fmac_f32_e32 v174, v177, v177
	v_lshlrev_b32_e32 v176, 16, v20
	v_and_b32_e32 v177, 0xffff0000, v20
	v_fmac_f32_e32 v174, v176, v176
	v_fmac_f32_e32 v174, v177, v177
	v_lshlrev_b32_e32 v176, 16, v21
	v_and_b32_e32 v177, 0xffff0000, v21
	v_fmac_f32_e32 v174, v176, v176
	v_fmac_f32_e32 v174, v177, v177
	v_lshlrev_b32_e32 v176, 16, v22
	v_and_b32_e32 v177, 0xffff0000, v22
	v_fmac_f32_e32 v174, v176, v176
	v_fmac_f32_e32 v174, v177, v177
	v_lshlrev_b32_e32 v176, 16, v23
	v_and_b32_e32 v177, 0xffff0000, v23
	v_fmac_f32_e32 v174, v176, v176
	v_fmac_f32_e32 v174, v177, v177
	v_lshlrev_b32_e32 v176, 16, v24
	v_and_b32_e32 v177, 0xffff0000, v24
	v_fmac_f32_e32 v174, v176, v176
	v_fmac_f32_e32 v174, v177, v177
	v_lshlrev_b32_e32 v176, 16, v25
	v_and_b32_e32 v177, 0xffff0000, v25
	v_fmac_f32_e32 v174, v176, v176
	v_fmac_f32_e32 v174, v177, v177
	v_lshlrev_b32_e32 v176, 16, v26
	v_and_b32_e32 v177, 0xffff0000, v26
	v_fmac_f32_e32 v174, v176, v176
	v_fmac_f32_e32 v174, v177, v177
	v_lshlrev_b32_e32 v176, 16, v27
	v_and_b32_e32 v177, 0xffff0000, v27
	v_fmac_f32_e32 v174, v176, v176
	v_fmac_f32_e32 v174, v177, v177
	v_lshlrev_b32_e32 v176, 16, v28
	v_and_b32_e32 v177, 0xffff0000, v28
	v_fmac_f32_e32 v174, v176, v176
	v_fmac_f32_e32 v174, v177, v177
	v_lshlrev_b32_e32 v176, 16, v29
	v_and_b32_e32 v177, 0xffff0000, v29
	v_fmac_f32_e32 v174, v176, v176
	v_fmac_f32_e32 v174, v177, v177
	v_lshlrev_b32_e32 v176, 16, v30
	v_and_b32_e32 v177, 0xffff0000, v30
	v_fmac_f32_e32 v174, v176, v176
	v_fmac_f32_e32 v174, v177, v177
	v_lshlrev_b32_e32 v176, 16, v31
	v_and_b32_e32 v177, 0xffff0000, v31
	v_fmac_f32_e32 v174, v176, v176
	v_fmac_f32_e32 v174, v177, v177
	v_lshlrev_b32_e32 v176, 16, v32
	v_and_b32_e32 v177, 0xffff0000, v32
	v_fmac_f32_e32 v174, v176, v176
	v_fmac_f32_e32 v174, v177, v177
	v_lshlrev_b32_e32 v176, 16, v33
	v_and_b32_e32 v177, 0xffff0000, v33
	v_fmac_f32_e32 v174, v176, v176
	v_fmac_f32_e32 v174, v177, v177
	v_mov_b32_e32 v176, 0x3c800000
	v_fma_f32 v174, v174, v176, v190
	v_rsq_f32_e32 v175, v174
	s_nop 0
	v_mul_f32_e32 v175, v175, v183
	s_waitcnt vmcnt(0)
	v_lshlrev_b32_e32 v178, 16, v2
	v_lshlrev_b32_e32 v179, 16, v10
	v_mul_f32_e32 v178, v178, v175
	v_mul_f32_e32 v179, v179, v175
	v_mul_f32_e32 v178, v178, v98
	v_mul_f32_e32 v179, v179, v114
	v_mul_f32_e32 v176, v179, v50
	v_fma_f32 v180, v178, v34, -v176
	v_mul_f32_e32 v176, v179, v34
	v_fma_f32 v181, v178, v50, v176
	v_and_b32_e32 v178, 0xffff0000, v2
	v_and_b32_e32 v179, 0xffff0000, v10
	v_mul_f32_e32 v178, v178, v175
	v_mul_f32_e32 v179, v179, v175
	v_mul_f32_e32 v178, v178, v99
	v_mul_f32_e32 v179, v179, v115
	v_mul_f32_e32 v176, v179, v51
	v_fma_f32 v182, v178, v35, -v176
	v_mul_f32_e32 v176, v179, v35
	v_fma_f32 v177, v178, v51, v176
	v_cvt_pk_bf16_f32 v2, v180, v182
	v_cvt_pk_bf16_f32 v10, v181, v177
	v_lshlrev_b32_e32 v178, 16, v3
	v_lshlrev_b32_e32 v179, 16, v11
	v_mul_f32_e32 v178, v178, v175
	v_mul_f32_e32 v179, v179, v175
	v_mul_f32_e32 v178, v178, v100
	v_mul_f32_e32 v179, v179, v116
	v_mul_f32_e32 v176, v179, v52
	v_fma_f32 v180, v178, v36, -v176
	v_mul_f32_e32 v176, v179, v36
	v_fma_f32 v181, v178, v52, v176
	v_and_b32_e32 v178, 0xffff0000, v3
	v_and_b32_e32 v179, 0xffff0000, v11
	v_mul_f32_e32 v178, v178, v175
	v_mul_f32_e32 v179, v179, v175
	v_mul_f32_e32 v178, v178, v101
	v_mul_f32_e32 v179, v179, v117
	v_mul_f32_e32 v176, v179, v53
	v_fma_f32 v182, v178, v37, -v176
	v_mul_f32_e32 v176, v179, v37
	v_fma_f32 v177, v178, v53, v176
	v_cvt_pk_bf16_f32 v3, v180, v182
	v_cvt_pk_bf16_f32 v11, v181, v177
	v_lshlrev_b32_e32 v178, 16, v4
	v_lshlrev_b32_e32 v179, 16, v12
	v_mul_f32_e32 v178, v178, v175
	v_mul_f32_e32 v179, v179, v175
	v_mul_f32_e32 v178, v178, v102
	v_mul_f32_e32 v179, v179, v118
	v_mul_f32_e32 v176, v179, v54
	v_fma_f32 v180, v178, v38, -v176
	v_mul_f32_e32 v176, v179, v38
	v_fma_f32 v181, v178, v54, v176
	v_and_b32_e32 v178, 0xffff0000, v4
	v_and_b32_e32 v179, 0xffff0000, v12
	v_mul_f32_e32 v178, v178, v175
	v_mul_f32_e32 v179, v179, v175
	v_mul_f32_e32 v178, v178, v103
	v_mul_f32_e32 v179, v179, v119
	v_mul_f32_e32 v176, v179, v55
	v_fma_f32 v182, v178, v39, -v176
	v_mul_f32_e32 v176, v179, v39
	v_fma_f32 v177, v178, v55, v176
	v_cvt_pk_bf16_f32 v4, v180, v182
	v_cvt_pk_bf16_f32 v12, v181, v177
	v_lshlrev_b32_e32 v178, 16, v5
	v_lshlrev_b32_e32 v179, 16, v13
	v_mul_f32_e32 v178, v178, v175
	v_mul_f32_e32 v179, v179, v175
	v_mul_f32_e32 v178, v178, v104
	v_mul_f32_e32 v179, v179, v120
	v_mul_f32_e32 v176, v179, v56
	v_fma_f32 v180, v178, v40, -v176
	v_mul_f32_e32 v176, v179, v40
	v_fma_f32 v181, v178, v56, v176
	v_and_b32_e32 v178, 0xffff0000, v5
	v_and_b32_e32 v179, 0xffff0000, v13
	v_mul_f32_e32 v178, v178, v175
	v_mul_f32_e32 v179, v179, v175
	v_mul_f32_e32 v178, v178, v105
	v_mul_f32_e32 v179, v179, v121
	v_mul_f32_e32 v176, v179, v57
	v_fma_f32 v182, v178, v41, -v176
	v_mul_f32_e32 v176, v179, v41
	v_fma_f32 v177, v178, v57, v176
	v_cvt_pk_bf16_f32 v5, v180, v182
	v_cvt_pk_bf16_f32 v13, v181, v177
	global_store_dwordx4 v171, v[2:5], s[12:13] offset:0
	global_store_dwordx4 v171, v[10:13], s[12:13] offset:32
; #define P_ROPE WSP(float, OFF_ROPE)
; DI unsigned pack2(float a, float b) { f2_t v = {a, b}; bf2_t r = __builtin_convertvector(v, bf2_t); return __builtin_bit_cast(unsigned, r); }
; #define BLO(u) __uint_as_float((u) << 16)
; #define BHI(u) __uint_as_float((u) & 0xffff0000u)
; DI void mla_item(const Params& p, int l, int item, char* smem) {
;     ...
;       for (int pi = 0; pi < 4; ++pi) {
;         const int c = (pi & 1) + (pi >> 1) * 4;
;         const float* tab = P_ROPE + ((pi >> 1) ? (pos & 63) : (pos >> 6)) * 32 + (pi & 1) * 8;
;         const float4 c0 = *(const float4*)(tab), c1 = *(const float4*)(tab + 4), s0 = *(const float4*)(tab + 16), s1 = *(const float4*)(tab + 20);
;         const float cs[8] = {c0.x, c0.y, c0.z, c0.w, c1.x, c1.y, c1.z, c1.w}, sn[8] = {s0.x, s0.y, s0.z, s0.w, s1.x, s1.y, s1.z, s1.w};
;         const float4 ga0 = *(const float4*)(g + c * 8), ga1 = *(const float4*)(g + c * 8 + 4), gb0 = *(const float4*)(g + c * 8 + 16), gb1 = *(const float4*)(g + c * 8 + 20);
;         const float ga[8] = {ga0.x, ga0.y, ga0.z, ga0.w, ga1.x, ga1.y, ga1.z, ga1.w}, gb[8] = {gb0.x, gb0.y, gb0.z, gb0.w, gb1.x, gb1.y, gb1.z, gb1.w};
;         const unsigned ua[4] = {q[c].x, q[c].y, q[c].z, q[c].w}, ub[4] = {q[c + 2].x, q[c + 2].y, q[c + 2].z, q[c + 2].w};
;         unsigned oa[4], ob[4];
; #pragma unroll
;         for (int e = 0; e < 4; ++e) {
;           const float x1l = BLO(ua[e]) * sc * ga[2 * e], x1h = BHI(ua[e]) * sc * ga[2 * e + 1];
;           const float x2l = BLO(ub[e]) * sc * gb[2 * e], x2h = BHI(ub[e]) * sc * gb[2 * e + 1];
;           oa[e] = pack2(x1l * cs[2 * e] - x2l * sn[2 * e], x1h * cs[2 * e + 1] - x2h * sn[2 * e + 1]);
;           ob[e] = pack2(x1l * sn[2 * e] + x2l * cs[2 * e], x1h * sn[2 * e + 1] + x2h * cs[2 * e + 1]);
;         }
;         uint4 wa, wb; wa.x = oa[0]; wa.y = oa[1]; wa.z = oa[2]; wa.w = oa[3]; wb.x = ob[0]; wb.y = ob[1]; wb.z = ob[2]; wb.w = ob[3];
;         *(uint4*)(hp + c * 8) = wa; *(uint4*)(hp + (c + 2) * 8) = wb;
;       }
	v_lshlrev_b32_e32 v178, 16, v6
	v_lshlrev_b32_e32 v179, 16, v14
	v_mul_f32_e32 v178, v178, v175
	v_mul_f32_e32 v179, v179, v175
	v_mul_f32_e32 v178, v178, v106
	v_mul_f32_e32 v179, v179, v122
	v_mul_f32_e32 v176, v179, v58
	v_fma_f32 v180, v178, v42, -v176
	v_mul_f32_e32 v176, v179, v42
	v_fma_f32 v181, v178, v58, v176
	v_and_b32_e32 v178, 0xffff0000, v6
	v_and_b32_e32 v179, 0xffff0000, v14
	v_mul_f32_e32 v178, v178, v175
	v_mul_f32_e32 v179, v179, v175
	v_mul_f32_e32 v178, v178, v107
	v_mul_f32_e32 v179, v179, v123
	v_mul_f32_e32 v176, v179, v59
	v_fma_f32 v182, v178, v43, -v176
	v_mul_f32_e32 v176, v179, v43
	v_fma_f32 v177, v178, v59, v176
	v_cvt_pk_bf16_f32 v6, v180, v182
	v_cvt_pk_bf16_f32 v14, v181, v177
	v_lshlrev_b32_e32 v178, 16, v7
	v_lshlrev_b32_e32 v179, 16, v15
	v_mul_f32_e32 v178, v178, v175
	v_mul_f32_e32 v179, v179, v175
	v_mul_f32_e32 v178, v178, v108
	v_mul_f32_e32 v179, v179, v124
	v_mul_f32_e32 v176, v179, v60
	v_fma_f32 v180, v178, v44, -v176
	v_mul_f32_e32 v176, v179, v44
	v_fma_f32 v181, v178, v60, v176
	v_and_b32_e32 v178, 0xffff0000, v7
	v_and_b32_e32 v179, 0xffff0000, v15
	v_mul_f32_e32 v178, v178, v175
	v_mul_f32_e32 v179, v179, v175
	v_mul_f32_e32 v178, v178, v109
	v_mul_f32_e32 v179, v179, v125
	v_mul_f32_e32 v176, v179, v61
	v_fma_f32 v182, v178, v45, -v176
	v_mul_f32_e32 v176, v179, v45
	v_fma_f32 v177, v178, v61, v176
	v_cvt_pk_bf16_f32 v7, v180, v182
	v_cvt_pk_bf16_f32 v15, v181, v177
	v_lshlrev_b32_e32 v178, 16, v8
	v_lshlrev_b32_e32 v179, 16, v16
	v_mul_f32_e32 v178, v178, v175
	v_mul_f32_e32 v179, v179, v175
	v_mul_f32_e32 v178, v178, v110
	v_mul_f32_e32 v179, v179, v126
	v_mul_f32_e32 v176, v179, v62
	v_fma_f32 v180, v178, v46, -v176
	v_mul_f32_e32 v176, v179, v46
	v_fma_f32 v181, v178, v62, v176
	v_and_b32_e32 v178, 0xffff0000, v8
	v_and_b32_e32 v179, 0xffff0000, v16
	v_mul_f32_e32 v178, v178, v175
	v_mul_f32_e32 v179, v179, v175
	v_mul_f32_e32 v178, v178, v111
	v_mul_f32_e32 v179, v179, v127
	v_mul_f32_e32 v176, v179, v63
	v_fma_f32 v182, v178, v47, -v176
	v_mul_f32_e32 v176, v179, v47
	v_fma_f32 v177, v178, v63, v176
	v_cvt_pk_bf16_f32 v8, v180, v182
	v_cvt_pk_bf16_f32 v16, v181, v177
	v_lshlrev_b32_e32 v178, 16, v9
	v_lshlrev_b32_e32 v179, 16, v17
	v_mul_f32_e32 v178, v178, v175
	v_mul_f32_e32 v179, v179, v175
	v_mul_f32_e32 v178, v178, v112
	v_mul_f32_e32 v179, v179, v128
	v_mul_f32_e32 v176, v179, v64
	v_fma_f32 v180, v178, v48, -v176
	v_mul_f32_e32 v176, v179, v48
	v_fma_f32 v181, v178, v64, v176
	v_and_b32_e32 v178, 0xffff0000, v9
	v_and_b32_e32 v179, 0xffff0000, v17
	v_mul_f32_e32 v178, v178, v175
	v_mul_f32_e32 v179, v179, v175
	v_mul_f32_e32 v178, v178, v113
	v_mul_f32_e32 v179, v179, v129
	v_mul_f32_e32 v176, v179, v65
	v_fma_f32 v182, v178, v49, -v176
	v_mul_f32_e32 v176, v179, v49
	v_fma_f32 v177, v178, v65, v176
	v_cvt_pk_bf16_f32 v9, v180, v182
	v_cvt_pk_bf16_f32 v17, v181, v177
	global_store_dwordx4 v171, v[6:9], s[12:13] offset:16
	global_store_dwordx4 v171, v[14:17], s[12:13] offset:48
	v_lshlrev_b32_e32 v178, 16, v18
	v_lshlrev_b32_e32 v179, 16, v26
	v_mul_f32_e32 v178, v178, v175
	v_mul_f32_e32 v179, v179, v175
	v_mul_f32_e32 v178, v178, v130
	v_mul_f32_e32 v179, v179, v146
	v_mul_f32_e32 v176, v179, v82
	v_fma_f32 v180, v178, v66, -v176
	v_mul_f32_e32 v176, v179, v66
	v_fma_f32 v181, v178, v82, v176
	v_and_b32_e32 v178, 0xffff0000, v18
	v_and_b32_e32 v179, 0xffff0000, v26
	v_mul_f32_e32 v178, v178, v175
	v_mul_f32_e32 v179, v179, v175
	v_mul_f32_e32 v178, v178, v131
	v_mul_f32_e32 v179, v179, v147
	v_mul_f32_e32 v176, v179, v83
	v_fma_f32 v182, v178, v67, -v176
	v_mul_f32_e32 v176, v179, v67
	v_fma_f32 v177, v178, v83, v176
	v_cvt_pk_bf16_f32 v18, v180, v182
	v_cvt_pk_bf16_f32 v26, v181, v177
	v_lshlrev_b32_e32 v178, 16, v19
	v_lshlrev_b32_e32 v179, 16, v27
	v_mul_f32_e32 v178, v178, v175
	v_mul_f32_e32 v179, v179, v175
	v_mul_f32_e32 v178, v178, v132
	v_mul_f32_e32 v179, v179, v148
	v_mul_f32_e32 v176, v179, v84
	v_fma_f32 v180, v178, v68, -v176
	v_mul_f32_e32 v176, v179, v68
	v_fma_f32 v181, v178, v84, v176
	v_and_b32_e32 v178, 0xffff0000, v19
	v_and_b32_e32 v179, 0xffff0000, v27
	v_mul_f32_e32 v178, v178, v175
	v_mul_f32_e32 v179, v179, v175
	v_mul_f32_e32 v178, v178, v133
	v_mul_f32_e32 v179, v179, v149
	v_mul_f32_e32 v176, v179, v85
	v_fma_f32 v182, v178, v69, -v176
	v_mul_f32_e32 v176, v179, v69
	v_fma_f32 v177, v178, v85, v176
	v_cvt_pk_bf16_f32 v19, v180, v182
	v_cvt_pk_bf16_f32 v27, v181, v177
	v_lshlrev_b32_e32 v178, 16, v20
	v_lshlrev_b32_e32 v179, 16, v28
	v_mul_f32_e32 v178, v178, v175
	v_mul_f32_e32 v179, v179, v175
	v_mul_f32_e32 v178, v178, v134
	v_mul_f32_e32 v179, v179, v158
	v_mul_f32_e32 v176, v179, v86
	v_fma_f32 v180, v178, v70, -v176
	v_mul_f32_e32 v176, v179, v70
	v_fma_f32 v181, v178, v86, v176
	v_and_b32_e32 v178, 0xffff0000, v20
	v_and_b32_e32 v179, 0xffff0000, v28
	v_mul_f32_e32 v178, v178, v175
	v_mul_f32_e32 v179, v179, v175
	v_mul_f32_e32 v178, v178, v135
	v_mul_f32_e32 v179, v179, v159
	v_mul_f32_e32 v176, v179, v87
	v_fma_f32 v182, v178, v71, -v176
	v_mul_f32_e32 v176, v179, v71
	v_fma_f32 v177, v178, v87, v176
	v_cvt_pk_bf16_f32 v20, v180, v182
	v_cvt_pk_bf16_f32 v28, v181, v177
	v_lshlrev_b32_e32 v178, 16, v21
	v_lshlrev_b32_e32 v179, 16, v29
	v_mul_f32_e32 v178, v178, v175
	v_mul_f32_e32 v179, v179, v175
	v_mul_f32_e32 v178, v178, v136
	v_mul_f32_e32 v179, v179, v160
	v_mul_f32_e32 v176, v179, v88
	v_fma_f32 v180, v178, v72, -v176
	v_mul_f32_e32 v176, v179, v72
	v_fma_f32 v181, v178, v88, v176
	v_and_b32_e32 v178, 0xffff0000, v21
	v_and_b32_e32 v179, 0xffff0000, v29
	v_mul_f32_e32 v178, v178, v175
	v_mul_f32_e32 v179, v179, v175
; #define P_ROPE WSP(float, OFF_ROPE)
; DI unsigned pack2(float a, float b) { f2_t v = {a, b}; bf2_t r = __builtin_convertvector(v, bf2_t); return __builtin_bit_cast(unsigned, r); }
; #define BLO(u) __uint_as_float((u) << 16)
; #define BHI(u) __uint_as_float((u) & 0xffff0000u)
; DI void mla_item(const Params& p, int l, int item, char* smem) {
;     ...
;       for (int pi = 0; pi < 4; ++pi) {
;         const int c = (pi & 1) + (pi >> 1) * 4;
;         const float* tab = P_ROPE + ((pi >> 1) ? (pos & 63) : (pos >> 6)) * 32 + (pi & 1) * 8;
;         const float4 c0 = *(const float4*)(tab), c1 = *(const float4*)(tab + 4), s0 = *(const float4*)(tab + 16), s1 = *(const float4*)(tab + 20);
;         const float cs[8] = {c0.x, c0.y, c0.z, c0.w, c1.x, c1.y, c1.z, c1.w}, sn[8] = {s0.x, s0.y, s0.z, s0.w, s1.x, s1.y, s1.z, s1.w};
;         const float4 ga0 = *(const float4*)(g + c * 8), ga1 = *(const float4*)(g + c * 8 + 4), gb0 = *(const float4*)(g + c * 8 + 16), gb1 = *(const float4*)(g + c * 8 + 20);
;         const float ga[8] = {ga0.x, ga0.y, ga0.z, ga0.w, ga1.x, ga1.y, ga1.z, ga1.w}, gb[8] = {gb0.x, gb0.y, gb0.z, gb0.w, gb1.x, gb1.y, gb1.z, gb1.w};
;         const unsigned ua[4] = {q[c].x, q[c].y, q[c].z, q[c].w}, ub[4] = {q[c + 2].x, q[c + 2].y, q[c + 2].z, q[c + 2].w};
;         unsigned oa[4], ob[4];
; #pragma unroll
;         for (int e = 0; e < 4; ++e) {
;           const float x1l = BLO(ua[e]) * sc * ga[2 * e], x1h = BHI(ua[e]) * sc * ga[2 * e + 1];
;           const float x2l = BLO(ub[e]) * sc * gb[2 * e], x2h = BHI(ub[e]) * sc * gb[2 * e + 1];
;           oa[e] = pack2(x1l * cs[2 * e] - x2l * sn[2 * e], x1h * cs[2 * e + 1] - x2h * sn[2 * e + 1]);
;           ob[e] = pack2(x1l * sn[2 * e] + x2l * cs[2 * e], x1h * sn[2 * e + 1] + x2h * cs[2 * e + 1]);
;         }
;         uint4 wa, wb; wa.x = oa[0]; wa.y = oa[1]; wa.z = oa[2]; wa.w = oa[3]; wb.x = ob[0]; wb.y = ob[1]; wb.z = ob[2]; wb.w = ob[3];
;         *(uint4*)(hp + c * 8) = wa; *(uint4*)(hp + (c + 2) * 8) = wb;
;       }
;     }
;     if (tid < 128) {
	v_mul_f32_e32 v178, v178, v137
	v_mul_f32_e32 v179, v179, v161
	v_mul_f32_e32 v176, v179, v89
	v_fma_f32 v182, v178, v73, -v176
	v_mul_f32_e32 v176, v179, v73
	v_fma_f32 v177, v178, v89, v176
	v_cvt_pk_bf16_f32 v21, v180, v182
	v_cvt_pk_bf16_f32 v29, v181, v177
	global_store_dwordx4 v171, v[18:21], s[12:13] offset:64
	global_store_dwordx4 v171, v[26:29], s[12:13] offset:96
	v_lshlrev_b32_e32 v178, 16, v22
	v_lshlrev_b32_e32 v179, 16, v30
	v_mul_f32_e32 v178, v178, v175
	v_mul_f32_e32 v179, v179, v175
	v_mul_f32_e32 v178, v178, v138
	v_mul_f32_e32 v179, v179, v162
	v_mul_f32_e32 v176, v179, v90
	v_fma_f32 v180, v178, v74, -v176
	v_mul_f32_e32 v176, v179, v74
	v_fma_f32 v181, v178, v90, v176
	v_and_b32_e32 v178, 0xffff0000, v22
	v_and_b32_e32 v179, 0xffff0000, v30
	v_mul_f32_e32 v178, v178, v175
	v_mul_f32_e32 v179, v179, v175
	v_mul_f32_e32 v178, v178, v139
	v_mul_f32_e32 v179, v179, v163
	v_mul_f32_e32 v176, v179, v91
	v_fma_f32 v182, v178, v75, -v176
	v_mul_f32_e32 v176, v179, v75
	v_fma_f32 v177, v178, v91, v176
	v_cvt_pk_bf16_f32 v22, v180, v182
	v_cvt_pk_bf16_f32 v30, v181, v177
	v_lshlrev_b32_e32 v178, 16, v23
	v_lshlrev_b32_e32 v179, 16, v31
	v_mul_f32_e32 v178, v178, v175
	v_mul_f32_e32 v179, v179, v175
	v_mul_f32_e32 v178, v178, v140
	v_mul_f32_e32 v179, v179, v164
	v_mul_f32_e32 v176, v179, v92
	v_fma_f32 v180, v178, v76, -v176
	v_mul_f32_e32 v176, v179, v76
	v_fma_f32 v181, v178, v92, v176
	v_and_b32_e32 v178, 0xffff0000, v23
	v_and_b32_e32 v179, 0xffff0000, v31
	v_mul_f32_e32 v178, v178, v175
	v_mul_f32_e32 v179, v179, v175
	v_mul_f32_e32 v178, v178, v141
	v_mul_f32_e32 v179, v179, v165
	v_mul_f32_e32 v176, v179, v93
	v_fma_f32 v182, v178, v77, -v176
	v_mul_f32_e32 v176, v179, v77
	v_fma_f32 v177, v178, v93, v176
	v_cvt_pk_bf16_f32 v23, v180, v182
	v_cvt_pk_bf16_f32 v31, v181, v177
	v_lshlrev_b32_e32 v178, 16, v24
	v_lshlrev_b32_e32 v179, 16, v32
	v_mul_f32_e32 v178, v178, v175
	v_mul_f32_e32 v179, v179, v175
	v_mul_f32_e32 v178, v178, v142
	v_mul_f32_e32 v179, v179, v166
	v_mul_f32_e32 v176, v179, v94
	v_fma_f32 v180, v178, v78, -v176
	v_mul_f32_e32 v176, v179, v78
	v_fma_f32 v181, v178, v94, v176
	v_and_b32_e32 v178, 0xffff0000, v24
	v_and_b32_e32 v179, 0xffff0000, v32
	v_mul_f32_e32 v178, v178, v175
	v_mul_f32_e32 v179, v179, v175
	v_mul_f32_e32 v178, v178, v143
	v_mul_f32_e32 v179, v179, v167
	v_mul_f32_e32 v176, v179, v95
	v_fma_f32 v182, v178, v79, -v176
	v_mul_f32_e32 v176, v179, v79
	v_fma_f32 v177, v178, v95, v176
	v_cvt_pk_bf16_f32 v24, v180, v182
	v_cvt_pk_bf16_f32 v32, v181, v177
	v_lshlrev_b32_e32 v178, 16, v25
	v_lshlrev_b32_e32 v179, 16, v33
	v_mul_f32_e32 v178, v178, v175
	v_mul_f32_e32 v179, v179, v175
	v_mul_f32_e32 v178, v178, v144
	v_mul_f32_e32 v179, v179, v168
	v_mul_f32_e32 v176, v179, v96
	v_fma_f32 v180, v178, v80, -v176
	v_mul_f32_e32 v176, v179, v80
	v_fma_f32 v181, v178, v96, v176
	v_and_b32_e32 v178, 0xffff0000, v25
	v_and_b32_e32 v179, 0xffff0000, v33
	v_mul_f32_e32 v178, v178, v175
	v_mul_f32_e32 v179, v179, v175
	v_mul_f32_e32 v178, v178, v145
	v_mul_f32_e32 v179, v179, v169
	v_mul_f32_e32 v176, v179, v97
	v_fma_f32 v182, v178, v81, -v176
	v_mul_f32_e32 v176, v179, v81
	v_fma_f32 v177, v178, v97, v176
	v_cvt_pk_bf16_f32 v25, v180, v182
	v_cvt_pk_bf16_f32 v33, v181, v177
	global_store_dwordx4 v171, v[22:25], s[12:13] offset:80
	global_store_dwordx4 v171, v[30:33], s[12:13] offset:112
	s_nop 1
	v_cmp_gt_u32_e32 vcc, s93, v188
	s_and_saveexec_b64 s[0:1], vcc
	s_cbranch_execz .Lmla_elem_done
; #define P_ROPE WSP(float, OFF_ROPE)
; DI unsigned pack2(float a, float b) { f2_t v = {a, b}; bf2_t r = __builtin_convertvector(v, bf2_t); return __builtin_bit_cast(unsigned, r); }
; #define BLO(u) __uint_as_float((u) << 16)
; #define BHI(u) __uint_as_float((u) & 0xffff0000u)
; DI void mla_item(const Params& p, int l, int item, char* smem) {
;     ...
;     if (tid < 128) {
;       const size_t t = (size_t)it * 128 + tid; const int pos = (int)(t & (SEQ - 1));
;       const bf16_t* src = P_PROJ + t * PW + C_AKR;
;       uint4 q[4];
; #pragma unroll
;       for (int c = 0; c < 4; ++c) q[c] = *(const uint4*)(src + c * 8);
;       uint4 w[4];
; #pragma unroll
;       for (int c = 0; c < 2; ++c) {
;         const float* tab = P_ROPE + pos * 32 + c * 8;
;         const float4 c0 = *(const float4*)(tab), c1 = *(const float4*)(tab + 4), s0 = *(const float4*)(tab + 16), s1 = *(const float4*)(tab + 20);
;         const float cs[8] = {c0.x, c0.y, c0.z, c0.w, c1.x, c1.y, c1.z, c1.w}, sn[8] = {s0.x, s0.y, s0.z, s0.w, s1.x, s1.y, s1.z, s1.w};
;         const unsigned ua[4] = {q[c].x, q[c].y, q[c].z, q[c].w}, ub[4] = {q[c + 2].x, q[c + 2].y, q[c + 2].z, q[c + 2].w};
;         unsigned oa[4], ob[4];
; #pragma unroll
;         for (int e = 0; e < 4; ++e) {
;           const float x1l = BLO(ua[e]), x1h = BHI(ua[e]), x2l = BLO(ub[e]), x2h = BHI(ub[e]);
;           oa[e] = pack2(x1l * cs[2 * e] - x2l * sn[2 * e], x1h * cs[2 * e + 1] - x2h * sn[2 * e + 1]);
;           ob[e] = pack2(x1l * sn[2 * e] + x2l * cs[2 * e], x1h * sn[2 * e + 1] + x2h * cs[2 * e + 1]);
;         }
;         w[c].x = oa[0]; w[c].y = oa[1]; w[c].z = oa[2]; w[c].w = oa[3];
;         w[c + 2].x = ob[0]; w[c + 2].y = ob[1]; w[c + 2].z = ob[2]; w[c + 2].w = ob[3];
;       }
; #pragma unroll
;       for (int h = 0; h < 4; ++h)
; #pragma unroll
;         for (int c = 0; c < 4; ++c) *(uint4*)(P_KA + t * 384 + h * 96 + 64 + c * 8) = w[c];
;     }
	v_add_u32_e32 v170, s22, v188
	v_mul_lo_u32 v171, v170, s4
	v_add_u32_e32 v171, 0x2500, v171
	global_load_dwordx4 v[2:5], v171, s[12:13] offset:0
	global_load_dwordx4 v[6:9], v171, s[12:13] offset:16
	global_load_dwordx4 v[10:13], v171, s[12:13] offset:32
	global_load_dwordx4 v[14:17], v171, s[12:13] offset:48
	v_and_b32_e32 v172, 0x1fff, v170
	v_lshlrev_b32_e32 v172, 7, v172
	global_load_dwordx4 v[34:37], v172, s[88:89] offset:0
	global_load_dwordx4 v[38:41], v172, s[88:89] offset:16
	global_load_dwordx4 v[42:45], v172, s[88:89] offset:32
	global_load_dwordx4 v[46:49], v172, s[88:89] offset:48
	global_load_dwordx4 v[50:53], v172, s[88:89] offset:64
	global_load_dwordx4 v[54:57], v172, s[88:89] offset:80
	global_load_dwordx4 v[58:61], v172, s[88:89] offset:96
	global_load_dwordx4 v[62:65], v172, s[88:89] offset:112
	s_add_u32 s28, s58, 0x1b4a4000
	s_addc_u32 s29, s59, 0
	v_mul_u32_u24_e32 v173, 0x300, v170
	s_waitcnt vmcnt(0)
	v_lshlrev_b32_e32 v178, 16, v2
	v_lshlrev_b32_e32 v179, 16, v10
	v_mul_f32_e32 v176, v179, v50
	v_fma_f32 v180, v178, v34, -v176
	v_mul_f32_e32 v176, v179, v34
	v_fma_f32 v181, v178, v50, v176
	v_and_b32_e32 v178, 0xffff0000, v2
	v_and_b32_e32 v179, 0xffff0000, v10
	v_mul_f32_e32 v176, v179, v51
	v_fma_f32 v182, v178, v35, -v176
	v_mul_f32_e32 v176, v179, v35
	v_fma_f32 v177, v178, v51, v176
	v_cvt_pk_bf16_f32 v2, v180, v182
	v_cvt_pk_bf16_f32 v10, v181, v177
	v_lshlrev_b32_e32 v178, 16, v3
	v_lshlrev_b32_e32 v179, 16, v11
	v_mul_f32_e32 v176, v179, v52
	v_fma_f32 v180, v178, v36, -v176
	v_mul_f32_e32 v176, v179, v36
	v_fma_f32 v181, v178, v52, v176
	v_and_b32_e32 v178, 0xffff0000, v3
	v_and_b32_e32 v179, 0xffff0000, v11
	v_mul_f32_e32 v176, v179, v53
	v_fma_f32 v182, v178, v37, -v176
	v_mul_f32_e32 v176, v179, v37
	v_fma_f32 v177, v178, v53, v176
	v_cvt_pk_bf16_f32 v3, v180, v182
	v_cvt_pk_bf16_f32 v11, v181, v177
	v_lshlrev_b32_e32 v178, 16, v4
	v_lshlrev_b32_e32 v179, 16, v12
	v_mul_f32_e32 v176, v179, v54
	v_fma_f32 v180, v178, v38, -v176
	v_mul_f32_e32 v176, v179, v38
	v_fma_f32 v181, v178, v54, v176
	v_and_b32_e32 v178, 0xffff0000, v4
	v_and_b32_e32 v179, 0xffff0000, v12
	v_mul_f32_e32 v176, v179, v55
	v_fma_f32 v182, v178, v39, -v176
	v_mul_f32_e32 v176, v179, v39
	v_fma_f32 v177, v178, v55, v176
	v_cvt_pk_bf16_f32 v4, v180, v182
	v_cvt_pk_bf16_f32 v12, v181, v177
	v_lshlrev_b32_e32 v178, 16, v5
	v_lshlrev_b32_e32 v179, 16, v13
	v_mul_f32_e32 v176, v179, v56
	v_fma_f32 v180, v178, v40, -v176
	v_mul_f32_e32 v176, v179, v40
	v_fma_f32 v181, v178, v56, v176
	v_and_b32_e32 v178, 0xffff0000, v5
	v_and_b32_e32 v179, 0xffff0000, v13
	v_mul_f32_e32 v176, v179, v57
	v_fma_f32 v182, v178, v41, -v176
	v_mul_f32_e32 v176, v179, v41
	v_fma_f32 v177, v178, v57, v176
	v_cvt_pk_bf16_f32 v5, v180, v182
	v_cvt_pk_bf16_f32 v13, v181, v177
	v_lshlrev_b32_e32 v178, 16, v6
	v_lshlrev_b32_e32 v179, 16, v14
	v_mul_f32_e32 v176, v179, v58
	v_fma_f32 v180, v178, v42, -v176
	v_mul_f32_e32 v176, v179, v42
	v_fma_f32 v181, v178, v58, v176
	v_and_b32_e32 v178, 0xffff0000, v6
	v_and_b32_e32 v179, 0xffff0000, v14
	v_mul_f32_e32 v176, v179, v59
	v_fma_f32 v182, v178, v43, -v176
	v_mul_f32_e32 v176, v179, v43
	v_fma_f32 v177, v178, v59, v176
	v_cvt_pk_bf16_f32 v6, v180, v182
	v_cvt_pk_bf16_f32 v14, v181, v177
	v_lshlrev_b32_e32 v178, 16, v7
	v_lshlrev_b32_e32 v179, 16, v15
	v_mul_f32_e32 v176, v179, v60
	v_fma_f32 v180, v178, v44, -v176
	v_mul_f32_e32 v176, v179, v44
	v_fma_f32 v181, v178, v60, v176
	v_and_b32_e32 v178, 0xffff0000, v7
	v_and_b32_e32 v179, 0xffff0000, v15
	v_mul_f32_e32 v176, v179, v61
	v_fma_f32 v182, v178, v45, -v176
	v_mul_f32_e32 v176, v179, v45
	v_fma_f32 v177, v178, v61, v176
	v_cvt_pk_bf16_f32 v7, v180, v182
	v_cvt_pk_bf16_f32 v15, v181, v177
	v_lshlrev_b32_e32 v178, 16, v8
	v_lshlrev_b32_e32 v179, 16, v16
	v_mul_f32_e32 v176, v179, v62
	v_fma_f32 v180, v178, v46, -v176
	v_mul_f32_e32 v176, v179, v46
	v_fma_f32 v181, v178, v62, v176
	v_and_b32_e32 v178, 0xffff0000, v8
	v_and_b32_e32 v179, 0xffff0000, v16
	v_mul_f32_e32 v176, v179, v63
	v_fma_f32 v182, v178, v47, -v176
	v_mul_f32_e32 v176, v179, v47
	v_fma_f32 v177, v178, v63, v176
	v_cvt_pk_bf16_f32 v8, v180, v182
	v_cvt_pk_bf16_f32 v16, v181, v177
	v_lshlrev_b32_e32 v178, 16, v9
	v_lshlrev_b32_e32 v179, 16, v17
	v_mul_f32_e32 v176, v179, v64
	v_fma_f32 v180, v178, v48, -v176
	v_mul_f32_e32 v176, v179, v48
	v_fma_f32 v181, v178, v64, v176
	v_and_b32_e32 v178, 0xffff0000, v9
	v_and_b32_e32 v179, 0xffff0000, v17
	v_mul_f32_e32 v176, v179, v65
	v_fma_f32 v182, v178, v49, -v176
	v_mul_f32_e32 v176, v179, v49
	v_fma_f32 v177, v178, v65, v176
	v_cvt_pk_bf16_f32 v9, v180, v182
	v_cvt_pk_bf16_f32 v17, v181, v177
	global_store_dwordx4 v173, v[2:5], s[28:29] offset:128
	global_store_dwordx4 v173, v[6:9], s[28:29] offset:144
	global_store_dwordx4 v173, v[10:13], s[28:29] offset:160
	global_store_dwordx4 v173, v[14:17], s[28:29] offset:176
	global_store_dwordx4 v173, v[2:5], s[28:29] offset:320
	global_store_dwordx4 v173, v[6:9], s[28:29] offset:336
	global_store_dwordx4 v173, v[10:13], s[28:29] offset:352
	global_store_dwordx4 v173, v[14:17], s[28:29] offset:368
	global_store_dwordx4 v173, v[2:5], s[28:29] offset:512
	global_store_dwordx4 v173, v[6:9], s[28:29] offset:528
	global_store_dwordx4 v173, v[10:13], s[28:29] offset:544
	global_store_dwordx4 v173, v[14:17], s[28:29] offset:560
	global_store_dwordx4 v173, v[2:5], s[28:29] offset:704
	global_store_dwordx4 v173, v[6:9], s[28:29] offset:720
	global_store_dwordx4 v173, v[10:13], s[28:29] offset:736
	global_store_dwordx4 v173, v[14:17], s[28:29] offset:752
.Lmla_elem_done:
.LBB0_216:
	s_or_b64 exec, exec, s[0:1]
	s_mov_b64 s[0:1], 0
